# K-loop MFMA segments: removed redundant lgkmcnt(0) after the barrier and the mid-cluster s_setprio 0/1 pair (20 sites each)
# speedup vs baseline: 1.0128x; 1.0038x over previous
.LBB0_315:
	s_add_u32 s2, s34, s0
	s_addc_u32 s3, s35, s1
	s_add_u32 s2, s2, 0x100
	s_addc_u32 s3, s3, 0
	s_add_u32 s7, s71, s0
	s_addc_u32 s8, s72, s1
	s_add_i32 s9, 0, 0x10000
	s_cmpk_eq_i32 s0, 0x700
	s_cselect_b32 s5, s59, s3
	s_cselect_b32 s4, s58, s2
	v_add_u32_e32 v0, s9, v190
	s_cselect_b32 s3, s27, s8
	s_cselect_b32 s2, s26, s7
	s_add_i32 s7, 0, 0x14000
	ds_read_b128 v[134:137], v0
	ds_read_b128 v[138:141], v0 offset:1024
	ds_read_b128 v[142:145], v0 offset:2048
	ds_read_b128 v[146:149], v0 offset:3072
	v_add_u32_e32 v0, s7, v190
	ds_read_b128 v[150:153], v0
	ds_read_b128 v[154:157], v0 offset:1024
	ds_read_b128 v[158:161], v0 offset:2048
	ds_read_b128 v[162:165], v0 offset:3072
	v_lshl_add_u64 v[186:187], v[132:133], 0, s[0:1]
	s_add_i32 m0, s15, 0xc000
	ds_read_b128 v[166:169], v191
	ds_read_b128 v[182:185], v191 offset:1024
	ds_read_b128 v[192:195], v191 offset:2048
	ds_read_b128 v[196:199], v191 offset:3072
	ds_read_b128 v[200:203], v191 offset:4096
	ds_read_b128 v[204:207], v191 offset:5120
	ds_read_b128 v[208:211], v191 offset:6144
	ds_read_b128 v[212:215], v191 offset:7168
	global_load_lds_dwordx4 v[186:187], off
	v_lshl_add_u64 v[186:187], v[130:131], 0, s[0:1]
	s_add_i32 m0, s15, 0xe000
	s_nop 0
	global_load_lds_dwordx4 v[186:187], off
	s_waitcnt vmcnt(8)
	s_waitcnt lgkmcnt(0)
	s_barrier
	s_setprio 1
	v_mfma_f32_16x16x32_bf16 v[126:129], v[134:137], v[166:169], v[126:129]
	v_mfma_f32_16x16x32_bf16 v[122:125], v[142:145], v[166:169], v[122:125]
	v_mfma_f32_16x16x32_bf16 v[118:121], v[134:137], v[192:195], v[118:121]
	v_mfma_f32_16x16x32_bf16 v[114:117], v[142:145], v[192:195], v[114:117]
	v_mfma_f32_16x16x32_bf16 v[110:113], v[134:137], v[200:203], v[110:113]
	v_mfma_f32_16x16x32_bf16 v[106:109], v[142:145], v[200:203], v[106:109]
	v_mfma_f32_16x16x32_bf16 v[102:105], v[134:137], v[208:211], v[102:105]
	v_mfma_f32_16x16x32_bf16 v[98:101], v[142:145], v[208:211], v[98:101]
	v_mfma_f32_16x16x32_bf16 v[126:129], v[138:141], v[182:185], v[126:129]
	v_mfma_f32_16x16x32_bf16 v[122:125], v[146:149], v[182:185], v[122:125]
	v_mfma_f32_16x16x32_bf16 v[118:121], v[138:141], v[196:199], v[118:121]
	v_mfma_f32_16x16x32_bf16 v[114:117], v[146:149], v[196:199], v[114:117]
	v_mfma_f32_16x16x32_bf16 v[110:113], v[138:141], v[204:207], v[110:113]
	v_mfma_f32_16x16x32_bf16 v[106:109], v[146:149], v[204:207], v[106:109]
	v_mfma_f32_16x16x32_bf16 v[102:105], v[138:141], v[212:215], v[102:105]
	v_mfma_f32_16x16x32_bf16 v[98:101], v[146:149], v[212:215], v[98:101]
	v_mfma_f32_16x16x32_bf16 v[94:97], v[150:153], v[166:169], v[94:97]
	v_mfma_f32_16x16x32_bf16 v[90:93], v[158:161], v[166:169], v[90:93]
	v_mfma_f32_16x16x32_bf16 v[86:89], v[150:153], v[192:195], v[86:89]
	v_mfma_f32_16x16x32_bf16 v[82:85], v[158:161], v[192:195], v[82:85]
	v_mfma_f32_16x16x32_bf16 v[78:81], v[150:153], v[200:203], v[78:81]
	v_mfma_f32_16x16x32_bf16 v[74:77], v[158:161], v[200:203], v[74:77]
	v_mfma_f32_16x16x32_bf16 v[70:73], v[150:153], v[208:211], v[70:73]
	v_mfma_f32_16x16x32_bf16 v[66:69], v[158:161], v[208:211], v[66:69]
	v_mfma_f32_16x16x32_bf16 v[94:97], v[154:157], v[182:185], v[94:97]
	v_mfma_f32_16x16x32_bf16 v[90:93], v[162:165], v[182:185], v[90:93]
	v_mfma_f32_16x16x32_bf16 v[86:89], v[154:157], v[196:199], v[86:89]
	v_mfma_f32_16x16x32_bf16 v[82:85], v[162:165], v[196:199], v[82:85]
	v_mfma_f32_16x16x32_bf16 v[78:81], v[154:157], v[204:207], v[78:81]
	v_mfma_f32_16x16x32_bf16 v[74:77], v[162:165], v[204:207], v[74:77]
	v_mfma_f32_16x16x32_bf16 v[70:73], v[154:157], v[212:215], v[70:73]
	v_mfma_f32_16x16x32_bf16 v[66:69], v[162:165], v[212:215], v[66:69]
	s_setprio 0
	s_barrier
	s_add_i32 s8, s9, s14
	v_lshl_add_u64 v[186:187], s[2:3], 0, v[170:171]
	s_mov_b32 m0, s8
	ds_read_b128 v[166:169], v191 offset:16384
	ds_read_b128 v[182:185], v191 offset:17408
	ds_read_b128 v[192:195], v191 offset:18432
	ds_read_b128 v[196:199], v191 offset:19456
	ds_read_b128 v[200:203], v191 offset:20480
	ds_read_b128 v[204:207], v191 offset:21504
	ds_read_b128 v[208:211], v191 offset:22528
	ds_read_b128 v[212:215], v191 offset:23552
	global_load_lds_dwordx4 v[186:187], off
	s_add_i32 m0, s8, 0x2000
	s_add_u32 s8, s2, 0x40000
	v_lshl_add_u64 v[236:237], s[2:3], 0, v[172:173]
	s_addc_u32 s9, s3, 0
	s_add_i32 s7, s7, s14
	global_load_lds_dwordx4 v[236:237], off
	v_lshl_add_u64 v[238:239], s[8:9], 0, v[170:171]
	s_mov_b32 m0, s7
	v_lshl_add_u64 v[244:245], s[4:5], 0, v[176:177]
	global_load_lds_dwordx4 v[238:239], off
	v_lshl_add_u64 v[238:239], s[8:9], 0, v[172:173]
	s_add_i32 m0, s7, 0x2000
	s_nop 0
	global_load_lds_dwordx4 v[238:239], off
	v_lshl_add_u64 v[238:239], s[4:5], 0, v[174:175]
	s_mov_b32 m0, s15
	s_nop 0
	global_load_lds_dwordx4 v[238:239], off
	s_mov_b32 m0, s17
	s_nop 0
	global_load_lds_dwordx4 v[244:245], off
	s_waitcnt vmcnt(8)
	s_waitcnt lgkmcnt(0)
	s_barrier
	s_setprio 1
	v_mfma_f32_16x16x32_bf16 v[62:65], v[134:137], v[166:169], v[62:65]
	v_mfma_f32_16x16x32_bf16 v[58:61], v[142:145], v[166:169], v[58:61]
	v_mfma_f32_16x16x32_bf16 v[54:57], v[134:137], v[192:195], v[54:57]
	v_mfma_f32_16x16x32_bf16 v[50:53], v[142:145], v[192:195], v[50:53]
	v_mfma_f32_16x16x32_bf16 v[46:49], v[134:137], v[200:203], v[46:49]
	v_mfma_f32_16x16x32_bf16 v[42:45], v[142:145], v[200:203], v[42:45]
	v_mfma_f32_16x16x32_bf16 v[38:41], v[134:137], v[208:211], v[38:41]
	v_mfma_f32_16x16x32_bf16 v[34:37], v[142:145], v[208:211], v[34:37]
	v_mfma_f32_16x16x32_bf16 v[62:65], v[138:141], v[182:185], v[62:65]
	v_mfma_f32_16x16x32_bf16 v[58:61], v[146:149], v[182:185], v[58:61]
	v_mfma_f32_16x16x32_bf16 v[54:57], v[138:141], v[196:199], v[54:57]
	v_mfma_f32_16x16x32_bf16 v[50:53], v[146:149], v[196:199], v[50:53]
	v_mfma_f32_16x16x32_bf16 v[46:49], v[138:141], v[204:207], v[46:49]
	v_mfma_f32_16x16x32_bf16 v[42:45], v[146:149], v[204:207], v[42:45]
	v_mfma_f32_16x16x32_bf16 v[38:41], v[138:141], v[212:215], v[38:41]
	v_mfma_f32_16x16x32_bf16 v[34:37], v[146:149], v[212:215], v[34:37]
	v_mfma_f32_16x16x32_bf16 v[30:33], v[150:153], v[166:169], v[30:33]
	v_mfma_f32_16x16x32_bf16 v[26:29], v[158:161], v[166:169], v[26:29]
	v_mfma_f32_16x16x32_bf16 v[22:25], v[150:153], v[192:195], v[22:25]
	v_mfma_f32_16x16x32_bf16 v[18:21], v[158:161], v[192:195], v[18:21]
	v_mfma_f32_16x16x32_bf16 v[14:17], v[150:153], v[200:203], v[14:17]
	v_mfma_f32_16x16x32_bf16 v[10:13], v[158:161], v[200:203], v[10:13]
	v_mfma_f32_16x16x32_bf16 v[6:9], v[150:153], v[208:211], v[6:9]
	v_mfma_f32_16x16x32_bf16 v[2:5], v[158:161], v[208:211], v[2:5]
	v_mfma_f32_16x16x32_bf16 v[30:33], v[154:157], v[182:185], v[30:33]
	v_mfma_f32_16x16x32_bf16 v[26:29], v[162:165], v[182:185], v[26:29]
	v_mfma_f32_16x16x32_bf16 v[22:25], v[154:157], v[196:199], v[22:25]
	v_mfma_f32_16x16x32_bf16 v[18:21], v[162:165], v[196:199], v[18:21]
	v_mfma_f32_16x16x32_bf16 v[14:17], v[154:157], v[204:207], v[14:17]
	v_mfma_f32_16x16x32_bf16 v[10:13], v[162:165], v[204:207], v[10:13]
	v_mfma_f32_16x16x32_bf16 v[6:9], v[154:157], v[212:215], v[6:9]
	v_mfma_f32_16x16x32_bf16 v[2:5], v[162:165], v[212:215], v[2:5]
	s_setprio 0
	s_barrier
	s_add_i32 s7, 0, 0x18000
	v_add_u32_e32 v0, s7, v190
	s_add_i32 s8, 0, 0x1c000
	ds_read_b128 v[134:137], v0
	ds_read_b128 v[138:141], v0 offset:1024
	ds_read_b128 v[142:145], v0 offset:2048
	ds_read_b128 v[146:149], v0 offset:3072
	v_add_u32_e32 v0, s8, v190
	ds_read_b128 v[150:153], v0
	ds_read_b128 v[154:157], v0 offset:1024
	ds_read_b128 v[158:161], v0 offset:2048
	ds_read_b128 v[162:165], v0 offset:3072
	s_add_u32 s4, s4, 0x40000
	s_addc_u32 s5, s5, 0
	s_mov_b32 m0, s19
	v_lshl_add_u64 v[246:247], s[4:5], 0, v[174:175]
	ds_read_b128 v[166:169], v191 offset:32768
	ds_read_b128 v[182:185], v191 offset:33792
	ds_read_b128 v[192:195], v191 offset:34816
	ds_read_b128 v[196:199], v191 offset:35840
	ds_read_b128 v[200:203], v191 offset:36864
	ds_read_b128 v[204:207], v191 offset:37888
	ds_read_b128 v[208:211], v191 offset:38912
	ds_read_b128 v[212:215], v191 offset:39936
	global_load_lds_dwordx4 v[246:247], off
	v_lshl_add_u64 v[246:247], s[4:5], 0, v[176:177]
	s_mov_b32 m0, s40
	s_nop 0
	global_load_lds_dwordx4 v[246:247], off
	s_waitcnt vmcnt(8)
	s_waitcnt lgkmcnt(0)
	s_barrier
	s_setprio 1
	v_mfma_f32_16x16x32_bf16 v[126:129], v[134:137], v[166:169], v[126:129]
	v_mfma_f32_16x16x32_bf16 v[122:125], v[142:145], v[166:169], v[122:125]
	v_mfma_f32_16x16x32_bf16 v[118:121], v[134:137], v[192:195], v[118:121]
	v_mfma_f32_16x16x32_bf16 v[114:117], v[142:145], v[192:195], v[114:117]
	v_mfma_f32_16x16x32_bf16 v[110:113], v[134:137], v[200:203], v[110:113]
	v_mfma_f32_16x16x32_bf16 v[106:109], v[142:145], v[200:203], v[106:109]
	v_mfma_f32_16x16x32_bf16 v[102:105], v[134:137], v[208:211], v[102:105]
	v_mfma_f32_16x16x32_bf16 v[98:101], v[142:145], v[208:211], v[98:101]
	v_mfma_f32_16x16x32_bf16 v[126:129], v[138:141], v[182:185], v[126:129]
	v_mfma_f32_16x16x32_bf16 v[122:125], v[146:149], v[182:185], v[122:125]
	v_mfma_f32_16x16x32_bf16 v[118:121], v[138:141], v[196:199], v[118:121]
	v_mfma_f32_16x16x32_bf16 v[114:117], v[146:149], v[196:199], v[114:117]
	v_mfma_f32_16x16x32_bf16 v[110:113], v[138:141], v[204:207], v[110:113]
	v_mfma_f32_16x16x32_bf16 v[106:109], v[146:149], v[204:207], v[106:109]
	v_mfma_f32_16x16x32_bf16 v[102:105], v[138:141], v[212:215], v[102:105]
	v_mfma_f32_16x16x32_bf16 v[98:101], v[146:149], v[212:215], v[98:101]
	v_mfma_f32_16x16x32_bf16 v[94:97], v[150:153], v[166:169], v[94:97]
	v_mfma_f32_16x16x32_bf16 v[90:93], v[158:161], v[166:169], v[90:93]
	v_mfma_f32_16x16x32_bf16 v[86:89], v[150:153], v[192:195], v[86:89]
	v_mfma_f32_16x16x32_bf16 v[82:85], v[158:161], v[192:195], v[82:85]
	v_mfma_f32_16x16x32_bf16 v[78:81], v[150:153], v[200:203], v[78:81]
	v_mfma_f32_16x16x32_bf16 v[74:77], v[158:161], v[200:203], v[74:77]
	v_mfma_f32_16x16x32_bf16 v[70:73], v[150:153], v[208:211], v[70:73]
	v_mfma_f32_16x16x32_bf16 v[66:69], v[158:161], v[208:211], v[66:69]
	v_mfma_f32_16x16x32_bf16 v[94:97], v[154:157], v[182:185], v[94:97]
	v_mfma_f32_16x16x32_bf16 v[90:93], v[162:165], v[182:185], v[90:93]
	v_mfma_f32_16x16x32_bf16 v[86:89], v[154:157], v[196:199], v[86:89]
	v_mfma_f32_16x16x32_bf16 v[82:85], v[162:165], v[196:199], v[82:85]
	v_mfma_f32_16x16x32_bf16 v[78:81], v[154:157], v[204:207], v[78:81]
	v_mfma_f32_16x16x32_bf16 v[74:77], v[162:165], v[204:207], v[74:77]
	v_mfma_f32_16x16x32_bf16 v[70:73], v[154:157], v[212:215], v[70:73]
	v_mfma_f32_16x16x32_bf16 v[66:69], v[162:165], v[212:215], v[66:69]
	s_setprio 0
	s_barrier
	s_add_i32 s4, s7, s14
	v_lshl_add_u64 v[186:187], v[186:187], 0, s[42:43]
	s_mov_b32 m0, s4
	ds_read_b128 v[166:169], v191 offset:49152
	ds_read_b128 v[182:185], v191 offset:50176
	ds_read_b128 v[192:195], v191 offset:51200
	ds_read_b128 v[196:199], v191 offset:52224
	ds_read_b128 v[200:203], v191 offset:53248
	ds_read_b128 v[204:207], v191 offset:54272
	ds_read_b128 v[208:211], v191 offset:55296
	ds_read_b128 v[212:215], v191 offset:56320
	global_load_lds_dwordx4 v[186:187], off
	s_add_i32 m0, s4, 0x2000
	s_add_u32 s2, s2, 0x40080
	v_lshl_add_u64 v[186:187], v[236:237], 0, s[42:43]
	s_addc_u32 s3, s3, 0
	s_add_i32 s4, s8, s14
	global_load_lds_dwordx4 v[186:187], off
	v_lshl_add_u64 v[186:187], s[2:3], 0, v[170:171]
	s_mov_b32 m0, s4
	s_nop 0
	global_load_lds_dwordx4 v[186:187], off
	v_lshl_add_u64 v[186:187], s[2:3], 0, v[172:173]
	s_add_i32 m0, s4, 0x2000
	s_nop 0
	global_load_lds_dwordx4 v[186:187], off
	v_lshl_add_u64 v[186:187], v[238:239], 0, s[42:43]
	s_mov_b32 m0, s50
	s_nop 0
	global_load_lds_dwordx4 v[186:187], off
	v_lshl_add_u64 v[186:187], v[244:245], 0, s[42:43]
	s_mov_b32 m0, s51
	s_nop 0
	global_load_lds_dwordx4 v[186:187], off
	s_waitcnt vmcnt(8)
	s_waitcnt lgkmcnt(0)
	s_barrier
	s_setprio 1
	v_mfma_f32_16x16x32_bf16 v[62:65], v[134:137], v[166:169], v[62:65]
	v_mfma_f32_16x16x32_bf16 v[58:61], v[142:145], v[166:169], v[58:61]
	v_mfma_f32_16x16x32_bf16 v[54:57], v[134:137], v[192:195], v[54:57]
	v_mfma_f32_16x16x32_bf16 v[50:53], v[142:145], v[192:195], v[50:53]
	v_mfma_f32_16x16x32_bf16 v[46:49], v[134:137], v[200:203], v[46:49]
	v_mfma_f32_16x16x32_bf16 v[42:45], v[142:145], v[200:203], v[42:45]
	v_mfma_f32_16x16x32_bf16 v[38:41], v[134:137], v[208:211], v[38:41]
	v_mfma_f32_16x16x32_bf16 v[34:37], v[142:145], v[208:211], v[34:37]
	v_mfma_f32_16x16x32_bf16 v[62:65], v[138:141], v[182:185], v[62:65]
	v_mfma_f32_16x16x32_bf16 v[58:61], v[146:149], v[182:185], v[58:61]
	v_mfma_f32_16x16x32_bf16 v[54:57], v[138:141], v[196:199], v[54:57]
	v_mfma_f32_16x16x32_bf16 v[50:53], v[146:149], v[196:199], v[50:53]
	v_mfma_f32_16x16x32_bf16 v[46:49], v[138:141], v[204:207], v[46:49]
	v_mfma_f32_16x16x32_bf16 v[42:45], v[146:149], v[204:207], v[42:45]
	v_mfma_f32_16x16x32_bf16 v[38:41], v[138:141], v[212:215], v[38:41]
	v_mfma_f32_16x16x32_bf16 v[34:37], v[146:149], v[212:215], v[34:37]
	v_mfma_f32_16x16x32_bf16 v[30:33], v[150:153], v[166:169], v[30:33]
	v_mfma_f32_16x16x32_bf16 v[26:29], v[158:161], v[166:169], v[26:29]
	v_mfma_f32_16x16x32_bf16 v[22:25], v[150:153], v[192:195], v[22:25]
	v_mfma_f32_16x16x32_bf16 v[18:21], v[158:161], v[192:195], v[18:21]
	v_mfma_f32_16x16x32_bf16 v[14:17], v[150:153], v[200:203], v[14:17]
	v_mfma_f32_16x16x32_bf16 v[10:13], v[158:161], v[200:203], v[10:13]
	v_mfma_f32_16x16x32_bf16 v[6:9], v[150:153], v[208:211], v[6:9]
	v_mfma_f32_16x16x32_bf16 v[2:5], v[158:161], v[208:211], v[2:5]
	v_mfma_f32_16x16x32_bf16 v[30:33], v[154:157], v[182:185], v[30:33]
	v_mfma_f32_16x16x32_bf16 v[26:29], v[162:165], v[182:185], v[26:29]
	v_mfma_f32_16x16x32_bf16 v[22:25], v[154:157], v[196:199], v[22:25]
	v_mfma_f32_16x16x32_bf16 v[18:21], v[162:165], v[196:199], v[18:21]
	v_mfma_f32_16x16x32_bf16 v[14:17], v[154:157], v[204:207], v[14:17]
	v_mfma_f32_16x16x32_bf16 v[10:13], v[162:165], v[204:207], v[10:13]
	v_mfma_f32_16x16x32_bf16 v[6:9], v[154:157], v[212:215], v[6:9]
	v_mfma_f32_16x16x32_bf16 v[2:5], v[162:165], v[212:215], v[2:5]
	s_setprio 0
	s_barrier
	s_add_i32 s6, s6, 2
	s_add_u32 s0, s0, 0x100
	s_addc_u32 s1, s1, 0
	s_cmp_gt_u32 s6, 13
	s_cbranch_scc0 .LBB0_315
	s_and_b64 vcc, exec, s[36:37]
	s_cbranch_vccz .LBB0_318
	s_barrier

.LBB0_350:
	s_add_u32 s2, s34, s0
	s_addc_u32 s3, s35, s1
	s_add_u32 s58, s36, s0
	s_addc_u32 s59, s37, s1
	s_add_i32 s60, 0, 0x10000
	s_cmp_eq_u32 s53, s57
	s_cselect_b32 s5, s39, s3
	s_cselect_b32 s4, s38, s2
	v_add_u32_e32 v0, s60, v247
	s_cselect_b32 s3, s47, s59
	s_cselect_b32 s2, s46, s58
	s_add_i32 s61, 0, 0x14000
	ds_read_b128 v[134:137], v0
	ds_read_b128 v[138:141], v0 offset:1024
	ds_read_b128 v[142:145], v0 offset:2048
	ds_read_b128 v[146:149], v0 offset:3072
	v_add_u32_e32 v0, s61, v247
	ds_read_b128 v[150:153], v0
	ds_read_b128 v[154:157], v0 offset:1024
	ds_read_b128 v[158:161], v0 offset:2048
	ds_read_b128 v[162:165], v0 offset:3072
	v_lshl_add_u64 v[194:195], s[34:35], 0, v[2:3]
	s_add_i32 m0, s11, 0xc000
	ds_read_b128 v[166:169], v248
	ds_read_b128 v[170:173], v248 offset:1024
	ds_read_b128 v[174:177], v248 offset:2048
	ds_read_b128 v[178:181], v248 offset:3072
	ds_read_b128 v[182:185], v248 offset:4096
	ds_read_b128 v[186:189], v248 offset:5120
	ds_read_b128 v[190:193], v248 offset:6144
	ds_read_b128 v[208:211], v248 offset:7168
	global_load_lds_dwordx4 v[194:195], off
	v_lshl_add_u64 v[194:195], s[34:35], 0, v[132:133]
	s_add_i32 m0, s11, 0xe000
	s_nop 0
	global_load_lds_dwordx4 v[194:195], off
	s_waitcnt vmcnt(8)
	s_waitcnt lgkmcnt(0)
	s_barrier
	s_setprio 1
	v_mfma_f32_16x16x32_bf16 v[128:131], v[134:137], v[166:169], v[128:131]
	v_mfma_f32_16x16x32_bf16 v[124:127], v[142:145], v[166:169], v[124:127]
	v_mfma_f32_16x16x32_bf16 v[120:123], v[134:137], v[174:177], v[120:123]
	v_mfma_f32_16x16x32_bf16 v[116:119], v[142:145], v[174:177], v[116:119]
	v_mfma_f32_16x16x32_bf16 v[112:115], v[134:137], v[182:185], v[112:115]
	v_mfma_f32_16x16x32_bf16 v[108:111], v[142:145], v[182:185], v[108:111]
	v_mfma_f32_16x16x32_bf16 v[104:107], v[134:137], v[190:193], v[104:107]
	v_mfma_f32_16x16x32_bf16 v[100:103], v[142:145], v[190:193], v[100:103]
	v_mfma_f32_16x16x32_bf16 v[128:131], v[138:141], v[170:173], v[128:131]
	v_mfma_f32_16x16x32_bf16 v[124:127], v[146:149], v[170:173], v[124:127]
	v_mfma_f32_16x16x32_bf16 v[120:123], v[138:141], v[178:181], v[120:123]
	v_mfma_f32_16x16x32_bf16 v[116:119], v[146:149], v[178:181], v[116:119]
	v_mfma_f32_16x16x32_bf16 v[112:115], v[138:141], v[186:189], v[112:115]
	v_mfma_f32_16x16x32_bf16 v[108:111], v[146:149], v[186:189], v[108:111]
	v_mfma_f32_16x16x32_bf16 v[104:107], v[138:141], v[208:211], v[104:107]
	v_mfma_f32_16x16x32_bf16 v[100:103], v[146:149], v[208:211], v[100:103]
	v_mfma_f32_16x16x32_bf16 v[96:99], v[150:153], v[166:169], v[96:99]
	v_mfma_f32_16x16x32_bf16 v[92:95], v[158:161], v[166:169], v[92:95]
	v_mfma_f32_16x16x32_bf16 v[88:91], v[150:153], v[174:177], v[88:91]
	v_mfma_f32_16x16x32_bf16 v[84:87], v[158:161], v[174:177], v[84:87]
	v_mfma_f32_16x16x32_bf16 v[80:83], v[150:153], v[182:185], v[80:83]
	v_mfma_f32_16x16x32_bf16 v[76:79], v[158:161], v[182:185], v[76:79]
	v_mfma_f32_16x16x32_bf16 v[72:75], v[150:153], v[190:193], v[72:75]
	v_mfma_f32_16x16x32_bf16 v[68:71], v[158:161], v[190:193], v[68:71]
	v_mfma_f32_16x16x32_bf16 v[96:99], v[154:157], v[170:173], v[96:99]
	v_mfma_f32_16x16x32_bf16 v[92:95], v[162:165], v[170:173], v[92:95]
	v_mfma_f32_16x16x32_bf16 v[88:91], v[154:157], v[178:181], v[88:91]
	v_mfma_f32_16x16x32_bf16 v[84:87], v[162:165], v[178:181], v[84:87]
	v_mfma_f32_16x16x32_bf16 v[80:83], v[154:157], v[186:189], v[80:83]
	v_mfma_f32_16x16x32_bf16 v[76:79], v[162:165], v[186:189], v[76:79]
	v_mfma_f32_16x16x32_bf16 v[72:75], v[154:157], v[208:211], v[72:75]
	v_mfma_f32_16x16x32_bf16 v[68:71], v[162:165], v[208:211], v[68:71]
	s_setprio 0
	s_barrier
	s_add_i32 s58, s60, s10
	v_lshl_add_u64 v[194:195], s[2:3], 0, v[196:197]
	s_mov_b32 m0, s58
	ds_read_b128 v[166:169], v248 offset:16384
	ds_read_b128 v[170:173], v248 offset:17408
	ds_read_b128 v[174:177], v248 offset:18432
	ds_read_b128 v[178:181], v248 offset:19456
	ds_read_b128 v[182:185], v248 offset:20480
	ds_read_b128 v[186:189], v248 offset:21504
	ds_read_b128 v[190:193], v248 offset:22528
	ds_read_b128 v[208:211], v248 offset:23552
	global_load_lds_dwordx4 v[194:195], off
	s_add_i32 m0, s58, 0x2000
	s_add_u32 s58, s2, 0x40000
	v_lshl_add_u64 v[212:213], s[2:3], 0, v[198:199]
	s_addc_u32 s59, s3, 0
	s_add_i32 s60, s61, s10
	global_load_lds_dwordx4 v[212:213], off
	v_lshl_add_u64 v[214:215], s[58:59], 0, v[196:197]
	s_mov_b32 m0, s60
	v_lshl_add_u64 v[236:237], s[4:5], 0, v[202:203]
	global_load_lds_dwordx4 v[214:215], off
	v_lshl_add_u64 v[214:215], s[58:59], 0, v[198:199]
	s_add_i32 m0, s60, 0x2000
	s_nop 0
	global_load_lds_dwordx4 v[214:215], off
	v_lshl_add_u64 v[214:215], s[4:5], 0, v[200:201]
	s_mov_b32 m0, s11
	s_nop 0
	global_load_lds_dwordx4 v[214:215], off
	s_mov_b32 m0, s14
	s_nop 0
	global_load_lds_dwordx4 v[236:237], off
	s_waitcnt vmcnt(8)
	s_waitcnt lgkmcnt(0)
	s_barrier
	s_setprio 1
	v_mfma_f32_16x16x32_bf16 v[64:67], v[134:137], v[166:169], v[64:67]
	v_mfma_f32_16x16x32_bf16 v[60:63], v[142:145], v[166:169], v[60:63]
	v_mfma_f32_16x16x32_bf16 v[56:59], v[134:137], v[174:177], v[56:59]
	v_mfma_f32_16x16x32_bf16 v[52:55], v[142:145], v[174:177], v[52:55]
	v_mfma_f32_16x16x32_bf16 v[48:51], v[134:137], v[182:185], v[48:51]
	v_mfma_f32_16x16x32_bf16 v[44:47], v[142:145], v[182:185], v[44:47]
	v_mfma_f32_16x16x32_bf16 v[40:43], v[134:137], v[190:193], v[40:43]
	v_mfma_f32_16x16x32_bf16 v[36:39], v[142:145], v[190:193], v[36:39]
	v_mfma_f32_16x16x32_bf16 v[64:67], v[138:141], v[170:173], v[64:67]
	v_mfma_f32_16x16x32_bf16 v[60:63], v[146:149], v[170:173], v[60:63]
	v_mfma_f32_16x16x32_bf16 v[56:59], v[138:141], v[178:181], v[56:59]
	v_mfma_f32_16x16x32_bf16 v[52:55], v[146:149], v[178:181], v[52:55]
	v_mfma_f32_16x16x32_bf16 v[48:51], v[138:141], v[186:189], v[48:51]
	v_mfma_f32_16x16x32_bf16 v[44:47], v[146:149], v[186:189], v[44:47]
	v_mfma_f32_16x16x32_bf16 v[40:43], v[138:141], v[208:211], v[40:43]
	v_mfma_f32_16x16x32_bf16 v[36:39], v[146:149], v[208:211], v[36:39]
	v_mfma_f32_16x16x32_bf16 v[32:35], v[150:153], v[166:169], v[32:35]
	v_mfma_f32_16x16x32_bf16 v[28:31], v[158:161], v[166:169], v[28:31]
	v_mfma_f32_16x16x32_bf16 v[24:27], v[150:153], v[174:177], v[24:27]
	v_mfma_f32_16x16x32_bf16 v[20:23], v[158:161], v[174:177], v[20:23]
	v_mfma_f32_16x16x32_bf16 v[16:19], v[150:153], v[182:185], v[16:19]
	v_mfma_f32_16x16x32_bf16 v[12:15], v[158:161], v[182:185], v[12:15]
	v_mfma_f32_16x16x32_bf16 v[8:11], v[150:153], v[190:193], v[8:11]
	v_mfma_f32_16x16x32_bf16 v[4:7], v[158:161], v[190:193], v[4:7]
	v_mfma_f32_16x16x32_bf16 v[32:35], v[154:157], v[170:173], v[32:35]
	v_mfma_f32_16x16x32_bf16 v[28:31], v[162:165], v[170:173], v[28:31]
	v_mfma_f32_16x16x32_bf16 v[24:27], v[154:157], v[178:181], v[24:27]
	v_mfma_f32_16x16x32_bf16 v[20:23], v[162:165], v[178:181], v[20:23]
	v_mfma_f32_16x16x32_bf16 v[16:19], v[154:157], v[186:189], v[16:19]
	v_mfma_f32_16x16x32_bf16 v[12:15], v[162:165], v[186:189], v[12:15]
	v_mfma_f32_16x16x32_bf16 v[8:11], v[154:157], v[208:211], v[8:11]
	v_mfma_f32_16x16x32_bf16 v[4:7], v[162:165], v[208:211], v[4:7]
	s_setprio 0
	s_barrier
	s_add_i32 s58, 0, 0x18000
	v_add_u32_e32 v0, s58, v247
	s_add_i32 s59, 0, 0x1c000
	ds_read_b128 v[134:137], v0
	ds_read_b128 v[138:141], v0 offset:1024
	ds_read_b128 v[142:145], v0 offset:2048
	ds_read_b128 v[146:149], v0 offset:3072
	v_add_u32_e32 v0, s59, v247
	ds_read_b128 v[150:153], v0
	ds_read_b128 v[154:157], v0 offset:1024
	ds_read_b128 v[158:161], v0 offset:2048
	ds_read_b128 v[162:165], v0 offset:3072
	s_add_u32 s4, s4, 0x40000
	s_addc_u32 s5, s5, 0
	s_mov_b32 m0, s15
	v_lshl_add_u64 v[238:239], s[4:5], 0, v[200:201]
	ds_read_b128 v[166:169], v248 offset:32768
	ds_read_b128 v[170:173], v248 offset:33792
	ds_read_b128 v[174:177], v248 offset:34816
	ds_read_b128 v[178:181], v248 offset:35840
	ds_read_b128 v[182:185], v248 offset:36864
	ds_read_b128 v[186:189], v248 offset:37888
	ds_read_b128 v[190:193], v248 offset:38912
	ds_read_b128 v[208:211], v248 offset:39936
	global_load_lds_dwordx4 v[238:239], off
	v_lshl_add_u64 v[238:239], s[4:5], 0, v[202:203]
	s_mov_b32 m0, s17
	s_nop 0
	global_load_lds_dwordx4 v[238:239], off
	s_waitcnt vmcnt(8)
	s_waitcnt lgkmcnt(0)
	s_barrier
	s_setprio 1
	v_mfma_f32_16x16x32_bf16 v[128:131], v[134:137], v[166:169], v[128:131]
	v_mfma_f32_16x16x32_bf16 v[124:127], v[142:145], v[166:169], v[124:127]
	v_mfma_f32_16x16x32_bf16 v[120:123], v[134:137], v[174:177], v[120:123]
	v_mfma_f32_16x16x32_bf16 v[116:119], v[142:145], v[174:177], v[116:119]
	v_mfma_f32_16x16x32_bf16 v[112:115], v[134:137], v[182:185], v[112:115]
	v_mfma_f32_16x16x32_bf16 v[108:111], v[142:145], v[182:185], v[108:111]
	v_mfma_f32_16x16x32_bf16 v[104:107], v[134:137], v[190:193], v[104:107]
	v_mfma_f32_16x16x32_bf16 v[100:103], v[142:145], v[190:193], v[100:103]
	v_mfma_f32_16x16x32_bf16 v[128:131], v[138:141], v[170:173], v[128:131]
	v_mfma_f32_16x16x32_bf16 v[124:127], v[146:149], v[170:173], v[124:127]
	v_mfma_f32_16x16x32_bf16 v[120:123], v[138:141], v[178:181], v[120:123]
	v_mfma_f32_16x16x32_bf16 v[116:119], v[146:149], v[178:181], v[116:119]
	v_mfma_f32_16x16x32_bf16 v[112:115], v[138:141], v[186:189], v[112:115]
	v_mfma_f32_16x16x32_bf16 v[108:111], v[146:149], v[186:189], v[108:111]
	v_mfma_f32_16x16x32_bf16 v[104:107], v[138:141], v[208:211], v[104:107]
	v_mfma_f32_16x16x32_bf16 v[100:103], v[146:149], v[208:211], v[100:103]
	v_mfma_f32_16x16x32_bf16 v[96:99], v[150:153], v[166:169], v[96:99]
	v_mfma_f32_16x16x32_bf16 v[92:95], v[158:161], v[166:169], v[92:95]
	v_mfma_f32_16x16x32_bf16 v[88:91], v[150:153], v[174:177], v[88:91]
	v_mfma_f32_16x16x32_bf16 v[84:87], v[158:161], v[174:177], v[84:87]
	v_mfma_f32_16x16x32_bf16 v[80:83], v[150:153], v[182:185], v[80:83]
	v_mfma_f32_16x16x32_bf16 v[76:79], v[158:161], v[182:185], v[76:79]
	v_mfma_f32_16x16x32_bf16 v[72:75], v[150:153], v[190:193], v[72:75]
	v_mfma_f32_16x16x32_bf16 v[68:71], v[158:161], v[190:193], v[68:71]
	v_mfma_f32_16x16x32_bf16 v[96:99], v[154:157], v[170:173], v[96:99]
	v_mfma_f32_16x16x32_bf16 v[92:95], v[162:165], v[170:173], v[92:95]
	v_mfma_f32_16x16x32_bf16 v[88:91], v[154:157], v[178:181], v[88:91]
	v_mfma_f32_16x16x32_bf16 v[84:87], v[162:165], v[178:181], v[84:87]
	v_mfma_f32_16x16x32_bf16 v[80:83], v[154:157], v[186:189], v[80:83]
	v_mfma_f32_16x16x32_bf16 v[76:79], v[162:165], v[186:189], v[76:79]
	v_mfma_f32_16x16x32_bf16 v[72:75], v[154:157], v[208:211], v[72:75]
	v_mfma_f32_16x16x32_bf16 v[68:71], v[162:165], v[208:211], v[68:71]
	s_setprio 0
	s_barrier
	s_add_i32 s4, s58, s10
	v_lshl_add_u64 v[194:195], v[194:195], 0, s[42:43]
	s_mov_b32 m0, s4
	ds_read_b128 v[166:169], v248 offset:49152
	ds_read_b128 v[170:173], v248 offset:50176
	ds_read_b128 v[174:177], v248 offset:51200
	ds_read_b128 v[178:181], v248 offset:52224
	ds_read_b128 v[182:185], v248 offset:53248
	ds_read_b128 v[186:189], v248 offset:54272
	ds_read_b128 v[190:193], v248 offset:55296
	ds_read_b128 v[208:211], v248 offset:56320
	global_load_lds_dwordx4 v[194:195], off
	s_add_i32 m0, s4, 0x2000
	s_add_u32 s2, s2, 0x40080
	v_lshl_add_u64 v[194:195], v[212:213], 0, s[42:43]
	s_addc_u32 s3, s3, 0
	s_add_i32 s4, s59, s10
	global_load_lds_dwordx4 v[194:195], off
	v_lshl_add_u64 v[194:195], s[2:3], 0, v[196:197]
	s_mov_b32 m0, s4
	s_nop 0
	global_load_lds_dwordx4 v[194:195], off
	v_lshl_add_u64 v[194:195], s[2:3], 0, v[198:199]
	s_add_i32 m0, s4, 0x2000
	s_nop 0
	global_load_lds_dwordx4 v[194:195], off
	v_lshl_add_u64 v[194:195], v[214:215], 0, s[42:43]
	s_mov_b32 m0, s41
	s_nop 0
	global_load_lds_dwordx4 v[194:195], off
	v_lshl_add_u64 v[194:195], v[236:237], 0, s[42:43]
	s_mov_b32 m0, s44
	s_nop 0
	global_load_lds_dwordx4 v[194:195], off
	s_waitcnt vmcnt(8)
	s_waitcnt lgkmcnt(0)
	s_barrier
	s_setprio 1
	v_mfma_f32_16x16x32_bf16 v[64:67], v[134:137], v[166:169], v[64:67]
	v_mfma_f32_16x16x32_bf16 v[60:63], v[142:145], v[166:169], v[60:63]
	v_mfma_f32_16x16x32_bf16 v[56:59], v[134:137], v[174:177], v[56:59]
	v_mfma_f32_16x16x32_bf16 v[52:55], v[142:145], v[174:177], v[52:55]
	v_mfma_f32_16x16x32_bf16 v[48:51], v[134:137], v[182:185], v[48:51]
	v_mfma_f32_16x16x32_bf16 v[44:47], v[142:145], v[182:185], v[44:47]
	v_mfma_f32_16x16x32_bf16 v[40:43], v[134:137], v[190:193], v[40:43]
	v_mfma_f32_16x16x32_bf16 v[36:39], v[142:145], v[190:193], v[36:39]
	v_mfma_f32_16x16x32_bf16 v[64:67], v[138:141], v[170:173], v[64:67]
	v_mfma_f32_16x16x32_bf16 v[60:63], v[146:149], v[170:173], v[60:63]
	v_mfma_f32_16x16x32_bf16 v[56:59], v[138:141], v[178:181], v[56:59]
	v_mfma_f32_16x16x32_bf16 v[52:55], v[146:149], v[178:181], v[52:55]
	v_mfma_f32_16x16x32_bf16 v[48:51], v[138:141], v[186:189], v[48:51]
	v_mfma_f32_16x16x32_bf16 v[44:47], v[146:149], v[186:189], v[44:47]
	v_mfma_f32_16x16x32_bf16 v[40:43], v[138:141], v[208:211], v[40:43]
	v_mfma_f32_16x16x32_bf16 v[36:39], v[146:149], v[208:211], v[36:39]
	v_mfma_f32_16x16x32_bf16 v[32:35], v[150:153], v[166:169], v[32:35]
	v_mfma_f32_16x16x32_bf16 v[28:31], v[158:161], v[166:169], v[28:31]
	v_mfma_f32_16x16x32_bf16 v[24:27], v[150:153], v[174:177], v[24:27]
	v_mfma_f32_16x16x32_bf16 v[20:23], v[158:161], v[174:177], v[20:23]
	v_mfma_f32_16x16x32_bf16 v[16:19], v[150:153], v[182:185], v[16:19]
	v_mfma_f32_16x16x32_bf16 v[12:15], v[158:161], v[182:185], v[12:15]
	v_mfma_f32_16x16x32_bf16 v[8:11], v[150:153], v[190:193], v[8:11]
	v_mfma_f32_16x16x32_bf16 v[4:7], v[158:161], v[190:193], v[4:7]
	v_mfma_f32_16x16x32_bf16 v[32:35], v[154:157], v[170:173], v[32:35]
	v_mfma_f32_16x16x32_bf16 v[28:31], v[162:165], v[170:173], v[28:31]
	v_mfma_f32_16x16x32_bf16 v[24:27], v[154:157], v[178:181], v[24:27]
	v_mfma_f32_16x16x32_bf16 v[20:23], v[162:165], v[178:181], v[20:23]
	v_mfma_f32_16x16x32_bf16 v[16:19], v[154:157], v[186:189], v[16:19]
	v_mfma_f32_16x16x32_bf16 v[12:15], v[162:165], v[186:189], v[12:15]
	v_mfma_f32_16x16x32_bf16 v[8:11], v[154:157], v[208:211], v[8:11]
	v_mfma_f32_16x16x32_bf16 v[4:7], v[162:165], v[208:211], v[4:7]
	s_setprio 0
	s_barrier
	s_add_i32 s2, s57, 2
	s_add_u32 s0, s0, 0x100
	s_addc_u32 s1, s1, 0
	v_lshl_add_u64 v[132:133], v[132:133], 0, s[62:63]
	v_lshl_add_u64 v[2:3], v[2:3], 0, s[62:63]
	s_cmp_ge_i32 s57, s53
	s_mov_b32 s57, s2
	s_cbranch_scc0 .LBB0_350
	s_and_b64 vcc, exec, s[26:27]
	s_cbranch_vccz .LBB0_353
	s_barrier

.LBB0_573:
	s_add_i32 s7, s2, 2
	s_add_u32 s8, s0, 0x80
	s_addc_u32 s3, s1, 0
	s_add_i32 s9, 0, 0x10000
	s_add_i32 s80, 0, 0x14000
	v_add_u32_e32 v0, s9, v212
	ds_read_b128 v[134:137], v0
	ds_read_b128 v[138:141], v0 offset:1024
	ds_read_b128 v[142:145], v0 offset:2048
	ds_read_b128 v[146:149], v0 offset:3072
	v_add_u32_e32 v0, s80, v212
	ds_read_b128 v[150:153], v0
	ds_read_b128 v[154:157], v0 offset:1024
	ds_read_b128 v[158:161], v0 offset:2048
	ds_read_b128 v[162:165], v0 offset:3072
	s_cmp_eq_u32 s4, s2
	s_cselect_b32 s2, s78, s8
	s_cselect_b32 s3, s79, s3
	s_cselect_b32 s8, s15, s55
	s_cselect_b32 s39, s77, s6
	s_cselect_b32 s38, s76, s5
	s_cselect_b32 s81, s17, s14
	v_lshl_add_u64 v[182:183], s[0:1], 0, v[132:133]
	s_add_i32 m0, s53, 0xc000
	ds_read_b128 v[166:169], v214
	ds_read_b128 v[170:173], v214 offset:1024
	ds_read_b128 v[174:177], v214 offset:2048
	ds_read_b128 v[178:181], v214 offset:3072
	ds_read_b128 v[188:191], v214 offset:4096
	ds_read_b128 v[192:195], v214 offset:5120
	ds_read_b128 v[196:199], v214 offset:6144
	ds_read_b128 v[200:203], v214 offset:7168
	global_load_lds_dwordx4 v[182:183], off
	v_lshl_add_u64 v[182:183], s[0:1], 0, v[2:3]
	s_add_i32 m0, s53, 0xe000
	s_nop 0
	global_load_lds_dwordx4 v[182:183], off
	s_waitcnt vmcnt(8)
	s_waitcnt lgkmcnt(0)
	s_barrier
	s_setprio 1
	v_mfma_f32_16x16x32_bf16 v[128:131], v[134:137], v[166:169], v[128:131]
	v_mfma_f32_16x16x32_bf16 v[124:127], v[142:145], v[166:169], v[124:127]
	v_mfma_f32_16x16x32_bf16 v[120:123], v[134:137], v[174:177], v[120:123]
	v_mfma_f32_16x16x32_bf16 v[116:119], v[142:145], v[174:177], v[116:119]
	v_mfma_f32_16x16x32_bf16 v[112:115], v[134:137], v[188:191], v[112:115]
	v_mfma_f32_16x16x32_bf16 v[108:111], v[142:145], v[188:191], v[108:111]
	v_mfma_f32_16x16x32_bf16 v[104:107], v[134:137], v[196:199], v[104:107]
	v_mfma_f32_16x16x32_bf16 v[100:103], v[142:145], v[196:199], v[100:103]
	v_mfma_f32_16x16x32_bf16 v[128:131], v[138:141], v[170:173], v[128:131]
	v_mfma_f32_16x16x32_bf16 v[124:127], v[146:149], v[170:173], v[124:127]
	v_mfma_f32_16x16x32_bf16 v[120:123], v[138:141], v[178:181], v[120:123]
	v_mfma_f32_16x16x32_bf16 v[116:119], v[146:149], v[178:181], v[116:119]
	v_mfma_f32_16x16x32_bf16 v[112:115], v[138:141], v[192:195], v[112:115]
	v_mfma_f32_16x16x32_bf16 v[108:111], v[146:149], v[192:195], v[108:111]
	v_mfma_f32_16x16x32_bf16 v[104:107], v[138:141], v[200:203], v[104:107]
	v_mfma_f32_16x16x32_bf16 v[100:103], v[146:149], v[200:203], v[100:103]
	v_mfma_f32_16x16x32_bf16 v[96:99], v[150:153], v[166:169], v[96:99]
	v_mfma_f32_16x16x32_bf16 v[92:95], v[158:161], v[166:169], v[92:95]
	v_mfma_f32_16x16x32_bf16 v[88:91], v[150:153], v[174:177], v[88:91]
	v_mfma_f32_16x16x32_bf16 v[84:87], v[158:161], v[174:177], v[84:87]
	v_mfma_f32_16x16x32_bf16 v[80:83], v[150:153], v[188:191], v[80:83]
	v_mfma_f32_16x16x32_bf16 v[76:79], v[158:161], v[188:191], v[76:79]
	v_mfma_f32_16x16x32_bf16 v[72:75], v[150:153], v[196:199], v[72:75]
	v_mfma_f32_16x16x32_bf16 v[68:71], v[158:161], v[196:199], v[68:71]
	v_mfma_f32_16x16x32_bf16 v[96:99], v[154:157], v[170:173], v[96:99]
	v_mfma_f32_16x16x32_bf16 v[92:95], v[162:165], v[170:173], v[92:95]
	v_mfma_f32_16x16x32_bf16 v[88:91], v[154:157], v[178:181], v[88:91]
	v_mfma_f32_16x16x32_bf16 v[84:87], v[162:165], v[178:181], v[84:87]
	v_mfma_f32_16x16x32_bf16 v[80:83], v[154:157], v[192:195], v[80:83]
	v_mfma_f32_16x16x32_bf16 v[76:79], v[162:165], v[192:195], v[76:79]
	v_mfma_f32_16x16x32_bf16 v[72:75], v[154:157], v[200:203], v[72:75]
	v_mfma_f32_16x16x32_bf16 v[68:71], v[162:165], v[200:203], v[68:71]
	s_setprio 0
	s_barrier
	s_add_i32 s9, s9, s52
	v_mad_u64_u32 v[182:183], s[46:47], s81, v187, v[184:185]
	s_mov_b32 m0, s9
	ds_read_b128 v[166:169], v214 offset:16384
	ds_read_b128 v[170:173], v214 offset:17408
	ds_read_b128 v[174:177], v214 offset:18432
	ds_read_b128 v[178:181], v214 offset:19456
	ds_read_b128 v[188:191], v214 offset:20480
	ds_read_b128 v[192:195], v214 offset:21504
	ds_read_b128 v[196:199], v214 offset:22528
	ds_read_b128 v[200:203], v214 offset:23552
	v_mov_b32_e32 v183, v1
	global_load_lds_dwordx4 v182, s[38:39]
	v_lshl_add_u32 v0, s81, 6, v182
	s_add_i32 m0, s9, 0x2000
	s_lshl_b32 s9, s81, 7
	v_lshl_add_u64 v[204:205], s[38:39], 0, v[182:183]
	v_lshl_add_u64 v[206:207], s[38:39], 0, v[0:1]
	global_load_lds_dwordx4 v0, s[38:39]
	s_add_u32 s38, s38, s9
	s_addc_u32 s39, s39, 0
	s_add_i32 s9, s80, s52
	s_mov_b32 m0, s9
	v_lshl_add_u64 v[208:209], s[38:39], 0, v[182:183]
	global_load_lds_dwordx4 v182, s[38:39]
	s_add_i32 m0, s9, 0x2000
	v_lshl_add_u64 v[182:183], s[38:39], 0, v[0:1]
	global_load_lds_dwordx4 v0, s[38:39]
	v_mad_u64_u32 v[236:237], s[38:39], s8, v185, v[184:185]
	s_mov_b32 m0, s53
	v_lshl_add_u32 v0, s8, 6, v236
	global_load_lds_dwordx4 v236, s[2:3]
	s_mov_b32 m0, s24
	v_mov_b32_e32 v237, v1
	global_load_lds_dwordx4 v0, s[2:3]
	s_waitcnt vmcnt(8)
	s_waitcnt lgkmcnt(0)
	v_lshl_add_u64 v[238:239], s[2:3], 0, v[236:237]
	v_lshl_add_u64 v[244:245], s[2:3], 0, v[0:1]
	s_barrier
	s_setprio 1
	v_mfma_f32_16x16x32_bf16 v[64:67], v[134:137], v[166:169], v[64:67]
	v_mfma_f32_16x16x32_bf16 v[60:63], v[142:145], v[166:169], v[60:63]
	v_mfma_f32_16x16x32_bf16 v[56:59], v[134:137], v[174:177], v[56:59]
	v_mfma_f32_16x16x32_bf16 v[52:55], v[142:145], v[174:177], v[52:55]
	v_mfma_f32_16x16x32_bf16 v[48:51], v[134:137], v[188:191], v[48:51]
	v_mfma_f32_16x16x32_bf16 v[44:47], v[142:145], v[188:191], v[44:47]
	v_mfma_f32_16x16x32_bf16 v[40:43], v[134:137], v[196:199], v[40:43]
	v_mfma_f32_16x16x32_bf16 v[36:39], v[142:145], v[196:199], v[36:39]
	v_mfma_f32_16x16x32_bf16 v[64:67], v[138:141], v[170:173], v[64:67]
	v_mfma_f32_16x16x32_bf16 v[60:63], v[146:149], v[170:173], v[60:63]
	v_mfma_f32_16x16x32_bf16 v[56:59], v[138:141], v[178:181], v[56:59]
	v_mfma_f32_16x16x32_bf16 v[52:55], v[146:149], v[178:181], v[52:55]
	v_mfma_f32_16x16x32_bf16 v[48:51], v[138:141], v[192:195], v[48:51]
	v_mfma_f32_16x16x32_bf16 v[44:47], v[146:149], v[192:195], v[44:47]
	v_mfma_f32_16x16x32_bf16 v[40:43], v[138:141], v[200:203], v[40:43]
	v_mfma_f32_16x16x32_bf16 v[36:39], v[146:149], v[200:203], v[36:39]
	v_mfma_f32_16x16x32_bf16 v[32:35], v[150:153], v[166:169], v[32:35]
	v_mfma_f32_16x16x32_bf16 v[28:31], v[158:161], v[166:169], v[28:31]
	v_mfma_f32_16x16x32_bf16 v[24:27], v[150:153], v[174:177], v[24:27]
	v_mfma_f32_16x16x32_bf16 v[20:23], v[158:161], v[174:177], v[20:23]
	v_mfma_f32_16x16x32_bf16 v[16:19], v[150:153], v[188:191], v[16:19]
	v_mfma_f32_16x16x32_bf16 v[12:15], v[158:161], v[188:191], v[12:15]
	v_mfma_f32_16x16x32_bf16 v[8:11], v[150:153], v[196:199], v[8:11]
	v_mfma_f32_16x16x32_bf16 v[4:7], v[158:161], v[196:199], v[4:7]
	v_mfma_f32_16x16x32_bf16 v[32:35], v[154:157], v[170:173], v[32:35]
	v_mfma_f32_16x16x32_bf16 v[28:31], v[162:165], v[170:173], v[28:31]
	v_mfma_f32_16x16x32_bf16 v[24:27], v[154:157], v[178:181], v[24:27]
	v_mfma_f32_16x16x32_bf16 v[20:23], v[162:165], v[178:181], v[20:23]
	v_mfma_f32_16x16x32_bf16 v[16:19], v[154:157], v[192:195], v[16:19]
	v_mfma_f32_16x16x32_bf16 v[12:15], v[162:165], v[192:195], v[12:15]
	v_mfma_f32_16x16x32_bf16 v[8:11], v[154:157], v[200:203], v[8:11]
	v_mfma_f32_16x16x32_bf16 v[4:7], v[162:165], v[200:203], v[4:7]
	s_setprio 0
	s_barrier
	s_add_i32 s9, 0, 0x18000
	s_add_i32 s38, 0, 0x1c000
	v_add_u32_e32 v146, s9, v212
	v_add_u32_e32 v162, s38, v212
	ds_read_b128 v[134:137], v146
	ds_read_b128 v[138:141], v146 offset:1024
	ds_read_b128 v[142:145], v146 offset:2048
	ds_read_b128 v[146:149], v146 offset:3072
	ds_read_b128 v[150:153], v162
	ds_read_b128 v[154:157], v162 offset:1024
	ds_read_b128 v[158:161], v162 offset:2048
	ds_read_b128 v[162:165], v162 offset:3072
	s_lshl_b32 s8, s8, 7
	s_add_u32 s2, s2, s8
	s_addc_u32 s3, s3, 0
	s_mov_b32 m0, s25
	ds_read_b128 v[166:169], v214 offset:32768
	ds_read_b128 v[170:173], v214 offset:33792
	ds_read_b128 v[174:177], v214 offset:34816
	ds_read_b128 v[178:181], v214 offset:35840
	ds_read_b128 v[188:191], v214 offset:36864
	ds_read_b128 v[192:195], v214 offset:37888
	ds_read_b128 v[196:199], v214 offset:38912
	ds_read_b128 v[200:203], v214 offset:39936
	global_load_lds_dwordx4 v236, s[2:3]
	s_mov_b32 m0, s48
	s_nop 0
	global_load_lds_dwordx4 v0, s[2:3]
	s_waitcnt vmcnt(8)
	s_waitcnt lgkmcnt(0)
	s_barrier
	s_setprio 1
	v_mfma_f32_16x16x32_bf16 v[128:131], v[134:137], v[166:169], v[128:131]
	v_mfma_f32_16x16x32_bf16 v[124:127], v[142:145], v[166:169], v[124:127]
	v_mfma_f32_16x16x32_bf16 v[120:123], v[134:137], v[174:177], v[120:123]
	v_mfma_f32_16x16x32_bf16 v[116:119], v[142:145], v[174:177], v[116:119]
	v_mfma_f32_16x16x32_bf16 v[112:115], v[134:137], v[188:191], v[112:115]
	v_mfma_f32_16x16x32_bf16 v[108:111], v[142:145], v[188:191], v[108:111]
	v_mfma_f32_16x16x32_bf16 v[104:107], v[134:137], v[196:199], v[104:107]
	v_mfma_f32_16x16x32_bf16 v[100:103], v[142:145], v[196:199], v[100:103]
	v_mfma_f32_16x16x32_bf16 v[128:131], v[138:141], v[170:173], v[128:131]
	v_mfma_f32_16x16x32_bf16 v[124:127], v[146:149], v[170:173], v[124:127]
	v_mfma_f32_16x16x32_bf16 v[120:123], v[138:141], v[178:181], v[120:123]
	v_mfma_f32_16x16x32_bf16 v[116:119], v[146:149], v[178:181], v[116:119]
	v_mfma_f32_16x16x32_bf16 v[112:115], v[138:141], v[192:195], v[112:115]
	v_mfma_f32_16x16x32_bf16 v[108:111], v[146:149], v[192:195], v[108:111]
	v_mfma_f32_16x16x32_bf16 v[104:107], v[138:141], v[200:203], v[104:107]
	v_mfma_f32_16x16x32_bf16 v[100:103], v[146:149], v[200:203], v[100:103]
	v_mfma_f32_16x16x32_bf16 v[96:99], v[150:153], v[166:169], v[96:99]
	v_mfma_f32_16x16x32_bf16 v[92:95], v[158:161], v[166:169], v[92:95]
	v_mfma_f32_16x16x32_bf16 v[88:91], v[150:153], v[174:177], v[88:91]
	v_mfma_f32_16x16x32_bf16 v[84:87], v[158:161], v[174:177], v[84:87]
	v_mfma_f32_16x16x32_bf16 v[80:83], v[150:153], v[188:191], v[80:83]
	v_mfma_f32_16x16x32_bf16 v[76:79], v[158:161], v[188:191], v[76:79]
	v_mfma_f32_16x16x32_bf16 v[72:75], v[150:153], v[196:199], v[72:75]
	v_mfma_f32_16x16x32_bf16 v[68:71], v[158:161], v[196:199], v[68:71]
	v_mfma_f32_16x16x32_bf16 v[96:99], v[154:157], v[170:173], v[96:99]
	v_mfma_f32_16x16x32_bf16 v[92:95], v[162:165], v[170:173], v[92:95]
	v_mfma_f32_16x16x32_bf16 v[88:91], v[154:157], v[178:181], v[88:91]
	v_mfma_f32_16x16x32_bf16 v[84:87], v[162:165], v[178:181], v[84:87]
	v_mfma_f32_16x16x32_bf16 v[80:83], v[154:157], v[192:195], v[80:83]
	v_mfma_f32_16x16x32_bf16 v[76:79], v[162:165], v[192:195], v[76:79]
	v_mfma_f32_16x16x32_bf16 v[72:75], v[154:157], v[200:203], v[72:75]
	v_mfma_f32_16x16x32_bf16 v[68:71], v[162:165], v[200:203], v[68:71]
	s_setprio 0
	s_barrier
	s_add_i32 s2, s9, s52
	v_lshl_add_u64 v[204:205], v[204:205], 0, s[42:43]
	s_mov_b32 m0, s2
	ds_read_b128 v[166:169], v214 offset:49152
	ds_read_b128 v[170:173], v214 offset:50176
	ds_read_b128 v[174:177], v214 offset:51200
	ds_read_b128 v[178:181], v214 offset:52224
	ds_read_b128 v[188:191], v214 offset:53248
	ds_read_b128 v[192:195], v214 offset:54272
	ds_read_b128 v[196:199], v214 offset:55296
	ds_read_b128 v[200:203], v214 offset:56320
	global_load_lds_dwordx4 v[204:205], off
	v_lshl_add_u64 v[204:205], v[206:207], 0, s[42:43]
	s_add_i32 m0, s2, 0x2000
	s_add_i32 s2, s38, s52
	global_load_lds_dwordx4 v[204:205], off
	v_lshl_add_u64 v[204:205], v[208:209], 0, s[42:43]
	s_mov_b32 m0, s2
	v_lshl_add_u64 v[182:183], v[182:183], 0, s[42:43]
	global_load_lds_dwordx4 v[204:205], off
	s_add_i32 m0, s2, 0x2000
	s_nop 0
	global_load_lds_dwordx4 v[182:183], off
	v_lshl_add_u64 v[182:183], v[238:239], 0, s[42:43]
	s_mov_b32 m0, s59
	s_nop 0
	global_load_lds_dwordx4 v[182:183], off
	v_lshl_add_u64 v[182:183], v[244:245], 0, s[42:43]
	s_mov_b32 m0, s56
	s_nop 0
	global_load_lds_dwordx4 v[182:183], off
	s_waitcnt vmcnt(8)
	s_waitcnt lgkmcnt(0)
	s_barrier
	s_setprio 1
	v_mfma_f32_16x16x32_bf16 v[64:67], v[134:137], v[166:169], v[64:67]
	v_mfma_f32_16x16x32_bf16 v[60:63], v[142:145], v[166:169], v[60:63]
	v_mfma_f32_16x16x32_bf16 v[56:59], v[134:137], v[174:177], v[56:59]
	v_mfma_f32_16x16x32_bf16 v[52:55], v[142:145], v[174:177], v[52:55]
	v_mfma_f32_16x16x32_bf16 v[48:51], v[134:137], v[188:191], v[48:51]
	v_mfma_f32_16x16x32_bf16 v[44:47], v[142:145], v[188:191], v[44:47]
	v_mfma_f32_16x16x32_bf16 v[40:43], v[134:137], v[196:199], v[40:43]
	v_mfma_f32_16x16x32_bf16 v[36:39], v[142:145], v[196:199], v[36:39]
	v_mfma_f32_16x16x32_bf16 v[64:67], v[138:141], v[170:173], v[64:67]
	v_mfma_f32_16x16x32_bf16 v[60:63], v[146:149], v[170:173], v[60:63]
	v_mfma_f32_16x16x32_bf16 v[56:59], v[138:141], v[178:181], v[56:59]
	v_mfma_f32_16x16x32_bf16 v[52:55], v[146:149], v[178:181], v[52:55]
	v_mfma_f32_16x16x32_bf16 v[48:51], v[138:141], v[192:195], v[48:51]
	v_mfma_f32_16x16x32_bf16 v[44:47], v[146:149], v[192:195], v[44:47]
	v_mfma_f32_16x16x32_bf16 v[40:43], v[138:141], v[200:203], v[40:43]
	v_mfma_f32_16x16x32_bf16 v[36:39], v[146:149], v[200:203], v[36:39]
	v_mfma_f32_16x16x32_bf16 v[32:35], v[150:153], v[166:169], v[32:35]
	v_mfma_f32_16x16x32_bf16 v[28:31], v[158:161], v[166:169], v[28:31]
	v_mfma_f32_16x16x32_bf16 v[24:27], v[150:153], v[174:177], v[24:27]
	v_mfma_f32_16x16x32_bf16 v[20:23], v[158:161], v[174:177], v[20:23]
	v_mfma_f32_16x16x32_bf16 v[16:19], v[150:153], v[188:191], v[16:19]
	v_mfma_f32_16x16x32_bf16 v[12:15], v[158:161], v[188:191], v[12:15]
	v_mfma_f32_16x16x32_bf16 v[8:11], v[150:153], v[196:199], v[8:11]
	v_mfma_f32_16x16x32_bf16 v[4:7], v[158:161], v[196:199], v[4:7]
	v_mfma_f32_16x16x32_bf16 v[32:35], v[154:157], v[170:173], v[32:35]
	v_mfma_f32_16x16x32_bf16 v[28:31], v[162:165], v[170:173], v[28:31]
	v_mfma_f32_16x16x32_bf16 v[24:27], v[154:157], v[178:181], v[24:27]
	v_mfma_f32_16x16x32_bf16 v[20:23], v[162:165], v[178:181], v[20:23]
	v_mfma_f32_16x16x32_bf16 v[16:19], v[154:157], v[192:195], v[16:19]
	v_mfma_f32_16x16x32_bf16 v[12:15], v[162:165], v[192:195], v[12:15]
	v_mfma_f32_16x16x32_bf16 v[8:11], v[154:157], v[200:203], v[8:11]
	v_mfma_f32_16x16x32_bf16 v[4:7], v[162:165], v[200:203], v[4:7]
	s_setprio 0
	s_barrier
	s_add_u32 s5, s5, 0x100
	s_addc_u32 s6, s6, 0
	s_add_u32 s0, s0, 0x100
	s_addc_u32 s1, s1, 0
	s_cmp_ge_i32 s7, s54
	s_mov_b32 s2, s7
	s_cbranch_scc0 .LBB0_573

.LBB0_913:
	s_add_i32 s35, s64, 2
	s_add_u32 s66, s62, 0x80
	s_addc_u32 s65, s63, 0
	s_add_i32 s67, 0, 0x10000
	s_add_i32 s88, 0, 0x14000
	v_add_u32_e32 v0, s67, v140
	ds_read_b128 v[144:147], v0
	ds_read_b128 v[148:151], v0 offset:1024
	ds_read_b128 v[152:155], v0 offset:2048
	ds_read_b128 v[156:159], v0 offset:3072
	v_add_u32_e32 v0, s88, v140
	ds_read_b128 v[160:163], v0
	ds_read_b128 v[164:167], v0 offset:1024
	ds_read_b128 v[168:171], v0 offset:2048
	ds_read_b128 v[172:175], v0 offset:3072
	s_cmp_eq_u32 s10, s64
	s_cselect_b32 s64, s60, s66
	s_cselect_b32 s65, s61, s65
	s_cselect_b32 s66, s74, s17
	s_cselect_b32 s69, s59, s15
	s_cselect_b32 s68, s58, s11
	s_cselect_b32 s89, s41, s40
	v_lshl_add_u64 v[208:209], s[62:63], 0, v[136:137]
	s_add_i32 m0, s76, 0xc000
	ds_read_b128 v[176:179], v142
	ds_read_b128 v[180:183], v142 offset:1024
	ds_read_b128 v[184:187], v142 offset:2048
	ds_read_b128 v[188:191], v142 offset:3072
	ds_read_b128 v[192:195], v142 offset:4096
	ds_read_b128 v[196:199], v142 offset:5120
	ds_read_b128 v[200:203], v142 offset:6144
	ds_read_b128 v[204:207], v142 offset:7168
	global_load_lds_dwordx4 v[208:209], off
	v_lshl_add_u64 v[208:209], s[62:63], 0, v[2:3]
	s_add_i32 m0, s76, 0xe000
	s_nop 0
	global_load_lds_dwordx4 v[208:209], off
	s_waitcnt vmcnt(8)
	s_waitcnt lgkmcnt(0)
	s_barrier
	s_setprio 1
	v_mfma_f32_16x16x32_bf16 v[128:131], v[144:147], v[176:179], v[128:131]
	v_mfma_f32_16x16x32_bf16 v[124:127], v[152:155], v[176:179], v[124:127]
	v_mfma_f32_16x16x32_bf16 v[120:123], v[144:147], v[184:187], v[120:123]
	v_mfma_f32_16x16x32_bf16 v[116:119], v[152:155], v[184:187], v[116:119]
	v_mfma_f32_16x16x32_bf16 v[112:115], v[144:147], v[192:195], v[112:115]
	v_mfma_f32_16x16x32_bf16 v[108:111], v[152:155], v[192:195], v[108:111]
	v_mfma_f32_16x16x32_bf16 v[104:107], v[144:147], v[200:203], v[104:107]
	v_mfma_f32_16x16x32_bf16 v[100:103], v[152:155], v[200:203], v[100:103]
	v_mfma_f32_16x16x32_bf16 v[128:131], v[148:151], v[180:183], v[128:131]
	v_mfma_f32_16x16x32_bf16 v[124:127], v[156:159], v[180:183], v[124:127]
	v_mfma_f32_16x16x32_bf16 v[120:123], v[148:151], v[188:191], v[120:123]
	v_mfma_f32_16x16x32_bf16 v[116:119], v[156:159], v[188:191], v[116:119]
	v_mfma_f32_16x16x32_bf16 v[112:115], v[148:151], v[196:199], v[112:115]
	v_mfma_f32_16x16x32_bf16 v[108:111], v[156:159], v[196:199], v[108:111]
	v_mfma_f32_16x16x32_bf16 v[104:107], v[148:151], v[204:207], v[104:107]
	v_mfma_f32_16x16x32_bf16 v[100:103], v[156:159], v[204:207], v[100:103]
	v_mfma_f32_16x16x32_bf16 v[96:99], v[160:163], v[176:179], v[96:99]
	v_mfma_f32_16x16x32_bf16 v[92:95], v[168:171], v[176:179], v[92:95]
	v_mfma_f32_16x16x32_bf16 v[88:91], v[160:163], v[184:187], v[88:91]
	v_mfma_f32_16x16x32_bf16 v[84:87], v[168:171], v[184:187], v[84:87]
	v_mfma_f32_16x16x32_bf16 v[80:83], v[160:163], v[192:195], v[80:83]
	v_mfma_f32_16x16x32_bf16 v[76:79], v[168:171], v[192:195], v[76:79]
	v_mfma_f32_16x16x32_bf16 v[72:75], v[160:163], v[200:203], v[72:75]
	v_mfma_f32_16x16x32_bf16 v[68:71], v[168:171], v[200:203], v[68:71]
	v_mfma_f32_16x16x32_bf16 v[96:99], v[164:167], v[180:183], v[96:99]
	v_mfma_f32_16x16x32_bf16 v[92:95], v[172:175], v[180:183], v[92:95]
	v_mfma_f32_16x16x32_bf16 v[88:91], v[164:167], v[188:191], v[88:91]
	v_mfma_f32_16x16x32_bf16 v[84:87], v[172:175], v[188:191], v[84:87]
	v_mfma_f32_16x16x32_bf16 v[80:83], v[164:167], v[196:199], v[80:83]
	v_mfma_f32_16x16x32_bf16 v[76:79], v[172:175], v[196:199], v[76:79]
	v_mfma_f32_16x16x32_bf16 v[72:75], v[164:167], v[204:207], v[72:75]
	v_mfma_f32_16x16x32_bf16 v[68:71], v[172:175], v[204:207], v[68:71]
	s_setprio 0
	s_barrier
	s_add_i32 s67, s67, s75
	v_mad_u64_u32 v[208:209], s[70:71], s89, v135, v[132:133]
	s_mov_b32 m0, s67
	ds_read_b128 v[176:179], v142 offset:16384
	ds_read_b128 v[180:183], v142 offset:17408
	ds_read_b128 v[184:187], v142 offset:18432
	ds_read_b128 v[188:191], v142 offset:19456
	ds_read_b128 v[192:195], v142 offset:20480
	ds_read_b128 v[196:199], v142 offset:21504
	ds_read_b128 v[200:203], v142 offset:22528
	ds_read_b128 v[204:207], v142 offset:23552
	v_mov_b32_e32 v209, v1
	global_load_lds_dwordx4 v208, s[68:69]
	v_lshl_add_u32 v0, s89, 6, v208
	s_add_i32 m0, s67, 0x2000
	s_lshl_b32 s67, s89, 7
	v_lshl_add_u64 v[210:211], s[68:69], 0, v[208:209]
	v_lshl_add_u64 v[212:213], s[68:69], 0, v[0:1]
	global_load_lds_dwordx4 v0, s[68:69]
	s_add_u32 s68, s68, s67
	s_addc_u32 s69, s69, 0
	s_add_i32 s67, s88, s75
	s_mov_b32 m0, s67
	v_lshl_add_u64 v[214:215], s[68:69], 0, v[208:209]
	global_load_lds_dwordx4 v208, s[68:69]
	s_add_i32 m0, s67, 0x2000
	v_lshl_add_u64 v[208:209], s[68:69], 0, v[0:1]
	global_load_lds_dwordx4 v0, s[68:69]
	v_mad_u64_u32 v[236:237], s[68:69], s66, v133, v[132:133]
	s_mov_b32 m0, s76
	v_lshl_add_u32 v0, s66, 6, v236
	global_load_lds_dwordx4 v236, s[64:65]
	s_mov_b32 m0, s77
	v_mov_b32_e32 v237, v1
	global_load_lds_dwordx4 v0, s[64:65]
	s_waitcnt vmcnt(8)
	s_waitcnt lgkmcnt(0)
	v_lshl_add_u64 v[238:239], s[64:65], 0, v[236:237]
	v_lshl_add_u64 v[244:245], s[64:65], 0, v[0:1]
	s_barrier
	s_setprio 1
	v_mfma_f32_16x16x32_bf16 v[64:67], v[144:147], v[176:179], v[64:67]
	v_mfma_f32_16x16x32_bf16 v[60:63], v[152:155], v[176:179], v[60:63]
	v_mfma_f32_16x16x32_bf16 v[56:59], v[144:147], v[184:187], v[56:59]
	v_mfma_f32_16x16x32_bf16 v[52:55], v[152:155], v[184:187], v[52:55]
	v_mfma_f32_16x16x32_bf16 v[48:51], v[144:147], v[192:195], v[48:51]
	v_mfma_f32_16x16x32_bf16 v[44:47], v[152:155], v[192:195], v[44:47]
	v_mfma_f32_16x16x32_bf16 v[40:43], v[144:147], v[200:203], v[40:43]
	v_mfma_f32_16x16x32_bf16 v[36:39], v[152:155], v[200:203], v[36:39]
	v_mfma_f32_16x16x32_bf16 v[64:67], v[148:151], v[180:183], v[64:67]
	v_mfma_f32_16x16x32_bf16 v[60:63], v[156:159], v[180:183], v[60:63]
	v_mfma_f32_16x16x32_bf16 v[56:59], v[148:151], v[188:191], v[56:59]
	v_mfma_f32_16x16x32_bf16 v[52:55], v[156:159], v[188:191], v[52:55]
	v_mfma_f32_16x16x32_bf16 v[48:51], v[148:151], v[196:199], v[48:51]
	v_mfma_f32_16x16x32_bf16 v[44:47], v[156:159], v[196:199], v[44:47]
	v_mfma_f32_16x16x32_bf16 v[40:43], v[148:151], v[204:207], v[40:43]
	v_mfma_f32_16x16x32_bf16 v[36:39], v[156:159], v[204:207], v[36:39]
	v_mfma_f32_16x16x32_bf16 v[32:35], v[160:163], v[176:179], v[32:35]
	v_mfma_f32_16x16x32_bf16 v[28:31], v[168:171], v[176:179], v[28:31]
	v_mfma_f32_16x16x32_bf16 v[24:27], v[160:163], v[184:187], v[24:27]
	v_mfma_f32_16x16x32_bf16 v[20:23], v[168:171], v[184:187], v[20:23]
	v_mfma_f32_16x16x32_bf16 v[16:19], v[160:163], v[192:195], v[16:19]
	v_mfma_f32_16x16x32_bf16 v[12:15], v[168:171], v[192:195], v[12:15]
	v_mfma_f32_16x16x32_bf16 v[8:11], v[160:163], v[200:203], v[8:11]
	v_mfma_f32_16x16x32_bf16 v[4:7], v[168:171], v[200:203], v[4:7]
	v_mfma_f32_16x16x32_bf16 v[32:35], v[164:167], v[180:183], v[32:35]
	v_mfma_f32_16x16x32_bf16 v[28:31], v[172:175], v[180:183], v[28:31]
	v_mfma_f32_16x16x32_bf16 v[24:27], v[164:167], v[188:191], v[24:27]
	v_mfma_f32_16x16x32_bf16 v[20:23], v[172:175], v[188:191], v[20:23]
	v_mfma_f32_16x16x32_bf16 v[16:19], v[164:167], v[196:199], v[16:19]
	v_mfma_f32_16x16x32_bf16 v[12:15], v[172:175], v[196:199], v[12:15]
	v_mfma_f32_16x16x32_bf16 v[8:11], v[164:167], v[204:207], v[8:11]
	v_mfma_f32_16x16x32_bf16 v[4:7], v[172:175], v[204:207], v[4:7]
	s_setprio 0
	s_barrier
	s_add_i32 s67, 0, 0x18000
	v_add_u32_e32 v143, s67, v140
	s_add_i32 s68, 0, 0x1c000
	ds_read_b128 v[144:147], v143
	ds_read_b128 v[148:151], v143 offset:1024
	ds_read_b128 v[152:155], v143 offset:2048
	ds_read_b128 v[156:159], v143 offset:3072
	v_add_u32_e32 v143, s68, v140
	ds_read_b128 v[160:163], v143
	ds_read_b128 v[164:167], v143 offset:1024
	ds_read_b128 v[168:171], v143 offset:2048
	ds_read_b128 v[172:175], v143 offset:3072
	s_lshl_b32 s66, s66, 7
	s_add_u32 s64, s64, s66
	s_addc_u32 s65, s65, 0
	s_mov_b32 m0, s78
	ds_read_b128 v[176:179], v142 offset:32768
	ds_read_b128 v[180:183], v142 offset:33792
	ds_read_b128 v[184:187], v142 offset:34816
	ds_read_b128 v[188:191], v142 offset:35840
	ds_read_b128 v[192:195], v142 offset:36864
	ds_read_b128 v[196:199], v142 offset:37888
	ds_read_b128 v[200:203], v142 offset:38912
	ds_read_b128 v[204:207], v142 offset:39936
	global_load_lds_dwordx4 v236, s[64:65]
	s_mov_b32 m0, s79
	s_nop 0
	global_load_lds_dwordx4 v0, s[64:65]
	s_waitcnt vmcnt(8)
	s_waitcnt lgkmcnt(0)
	s_barrier
	s_setprio 1
	v_mfma_f32_16x16x32_bf16 v[128:131], v[144:147], v[176:179], v[128:131]
	v_mfma_f32_16x16x32_bf16 v[124:127], v[152:155], v[176:179], v[124:127]
	v_mfma_f32_16x16x32_bf16 v[120:123], v[144:147], v[184:187], v[120:123]
	v_mfma_f32_16x16x32_bf16 v[116:119], v[152:155], v[184:187], v[116:119]
	v_mfma_f32_16x16x32_bf16 v[112:115], v[144:147], v[192:195], v[112:115]
	v_mfma_f32_16x16x32_bf16 v[108:111], v[152:155], v[192:195], v[108:111]
	v_mfma_f32_16x16x32_bf16 v[104:107], v[144:147], v[200:203], v[104:107]
	v_mfma_f32_16x16x32_bf16 v[100:103], v[152:155], v[200:203], v[100:103]
	v_mfma_f32_16x16x32_bf16 v[128:131], v[148:151], v[180:183], v[128:131]
	v_mfma_f32_16x16x32_bf16 v[124:127], v[156:159], v[180:183], v[124:127]
	v_mfma_f32_16x16x32_bf16 v[120:123], v[148:151], v[188:191], v[120:123]
	v_mfma_f32_16x16x32_bf16 v[116:119], v[156:159], v[188:191], v[116:119]
	v_mfma_f32_16x16x32_bf16 v[112:115], v[148:151], v[196:199], v[112:115]
	v_mfma_f32_16x16x32_bf16 v[108:111], v[156:159], v[196:199], v[108:111]
	v_mfma_f32_16x16x32_bf16 v[104:107], v[148:151], v[204:207], v[104:107]
	v_mfma_f32_16x16x32_bf16 v[100:103], v[156:159], v[204:207], v[100:103]
	v_mfma_f32_16x16x32_bf16 v[96:99], v[160:163], v[176:179], v[96:99]
	v_mfma_f32_16x16x32_bf16 v[92:95], v[168:171], v[176:179], v[92:95]
	v_mfma_f32_16x16x32_bf16 v[88:91], v[160:163], v[184:187], v[88:91]
	v_mfma_f32_16x16x32_bf16 v[84:87], v[168:171], v[184:187], v[84:87]
	v_mfma_f32_16x16x32_bf16 v[80:83], v[160:163], v[192:195], v[80:83]
	v_mfma_f32_16x16x32_bf16 v[76:79], v[168:171], v[192:195], v[76:79]
	v_mfma_f32_16x16x32_bf16 v[72:75], v[160:163], v[200:203], v[72:75]
	v_mfma_f32_16x16x32_bf16 v[68:71], v[168:171], v[200:203], v[68:71]
	v_mfma_f32_16x16x32_bf16 v[96:99], v[164:167], v[180:183], v[96:99]
	v_mfma_f32_16x16x32_bf16 v[92:95], v[172:175], v[180:183], v[92:95]
	v_mfma_f32_16x16x32_bf16 v[88:91], v[164:167], v[188:191], v[88:91]
	v_mfma_f32_16x16x32_bf16 v[84:87], v[172:175], v[188:191], v[84:87]
	v_mfma_f32_16x16x32_bf16 v[80:83], v[164:167], v[196:199], v[80:83]
	v_mfma_f32_16x16x32_bf16 v[76:79], v[172:175], v[196:199], v[76:79]
	v_mfma_f32_16x16x32_bf16 v[72:75], v[164:167], v[204:207], v[72:75]
	v_mfma_f32_16x16x32_bf16 v[68:71], v[172:175], v[204:207], v[68:71]
	s_setprio 0
	s_barrier
	s_add_i32 s64, s67, s75
	v_lshl_add_u64 v[210:211], v[210:211], 0, s[42:43]
	s_mov_b32 m0, s64
	ds_read_b128 v[176:179], v142 offset:49152
	ds_read_b128 v[180:183], v142 offset:50176
	ds_read_b128 v[184:187], v142 offset:51200
	ds_read_b128 v[188:191], v142 offset:52224
	ds_read_b128 v[192:195], v142 offset:53248
	ds_read_b128 v[196:199], v142 offset:54272
	ds_read_b128 v[200:203], v142 offset:55296
	ds_read_b128 v[204:207], v142 offset:56320
	global_load_lds_dwordx4 v[210:211], off
	v_lshl_add_u64 v[210:211], v[212:213], 0, s[42:43]
	s_add_i32 m0, s64, 0x2000
	s_add_i32 s64, s68, s75
	global_load_lds_dwordx4 v[210:211], off
	v_lshl_add_u64 v[210:211], v[214:215], 0, s[42:43]
	s_mov_b32 m0, s64
	v_lshl_add_u64 v[208:209], v[208:209], 0, s[42:43]
	global_load_lds_dwordx4 v[210:211], off
	s_add_i32 m0, s64, 0x2000
	s_nop 0
	global_load_lds_dwordx4 v[208:209], off
	v_lshl_add_u64 v[208:209], v[238:239], 0, s[42:43]
	s_mov_b32 m0, s82
	s_nop 0
	global_load_lds_dwordx4 v[208:209], off
	v_lshl_add_u64 v[208:209], v[244:245], 0, s[42:43]
	s_mov_b32 m0, s83
	s_nop 0
	global_load_lds_dwordx4 v[208:209], off
	s_waitcnt vmcnt(8)
	s_waitcnt lgkmcnt(0)
	s_barrier
	s_setprio 1
	v_mfma_f32_16x16x32_bf16 v[64:67], v[144:147], v[176:179], v[64:67]
	v_mfma_f32_16x16x32_bf16 v[60:63], v[152:155], v[176:179], v[60:63]
	v_mfma_f32_16x16x32_bf16 v[56:59], v[144:147], v[184:187], v[56:59]
	v_mfma_f32_16x16x32_bf16 v[52:55], v[152:155], v[184:187], v[52:55]
	v_mfma_f32_16x16x32_bf16 v[48:51], v[144:147], v[192:195], v[48:51]
	v_mfma_f32_16x16x32_bf16 v[44:47], v[152:155], v[192:195], v[44:47]
	v_mfma_f32_16x16x32_bf16 v[40:43], v[144:147], v[200:203], v[40:43]
	v_mfma_f32_16x16x32_bf16 v[36:39], v[152:155], v[200:203], v[36:39]
	v_mfma_f32_16x16x32_bf16 v[64:67], v[148:151], v[180:183], v[64:67]
	v_mfma_f32_16x16x32_bf16 v[60:63], v[156:159], v[180:183], v[60:63]
	v_mfma_f32_16x16x32_bf16 v[56:59], v[148:151], v[188:191], v[56:59]
	v_mfma_f32_16x16x32_bf16 v[52:55], v[156:159], v[188:191], v[52:55]
	v_mfma_f32_16x16x32_bf16 v[48:51], v[148:151], v[196:199], v[48:51]
	v_mfma_f32_16x16x32_bf16 v[44:47], v[156:159], v[196:199], v[44:47]
	v_mfma_f32_16x16x32_bf16 v[40:43], v[148:151], v[204:207], v[40:43]
	v_mfma_f32_16x16x32_bf16 v[36:39], v[156:159], v[204:207], v[36:39]
	v_mfma_f32_16x16x32_bf16 v[32:35], v[160:163], v[176:179], v[32:35]
	v_mfma_f32_16x16x32_bf16 v[28:31], v[168:171], v[176:179], v[28:31]
	v_mfma_f32_16x16x32_bf16 v[24:27], v[160:163], v[184:187], v[24:27]
	v_mfma_f32_16x16x32_bf16 v[20:23], v[168:171], v[184:187], v[20:23]
	v_mfma_f32_16x16x32_bf16 v[16:19], v[160:163], v[192:195], v[16:19]
	v_mfma_f32_16x16x32_bf16 v[12:15], v[168:171], v[192:195], v[12:15]
	v_mfma_f32_16x16x32_bf16 v[8:11], v[160:163], v[200:203], v[8:11]
	v_mfma_f32_16x16x32_bf16 v[4:7], v[168:171], v[200:203], v[4:7]
	v_mfma_f32_16x16x32_bf16 v[32:35], v[164:167], v[180:183], v[32:35]
	v_mfma_f32_16x16x32_bf16 v[28:31], v[172:175], v[180:183], v[28:31]
	v_mfma_f32_16x16x32_bf16 v[24:27], v[164:167], v[188:191], v[24:27]
	v_mfma_f32_16x16x32_bf16 v[20:23], v[172:175], v[188:191], v[20:23]
	v_mfma_f32_16x16x32_bf16 v[16:19], v[164:167], v[196:199], v[16:19]
	v_mfma_f32_16x16x32_bf16 v[12:15], v[172:175], v[196:199], v[12:15]
	v_mfma_f32_16x16x32_bf16 v[8:11], v[164:167], v[204:207], v[8:11]
	v_mfma_f32_16x16x32_bf16 v[4:7], v[172:175], v[204:207], v[4:7]
	s_setprio 0
	s_barrier
	s_add_u32 s11, s11, 0x100
	s_addc_u32 s15, s15, 0
	s_add_u32 s62, s62, 0x100
	s_addc_u32 s63, s63, 0
	s_cmp_ge_i32 s35, s44
	s_mov_b32 s64, s35
	s_cbranch_scc0 .LBB0_913

.LBB0_1026:
	s_add_u32 s2, s14, s0
	s_addc_u32 s3, s15, s1
	s_add_u32 s2, s2, 0x100
	s_addc_u32 s3, s3, 0
	s_add_u32 s7, s74, s0
	s_addc_u32 s37, s75, s1
	s_add_i32 s80, 0, 0x10000
	s_add_i32 s81, 0, 0x14000
	v_add_u32_e32 v0, s80, v180
	ds_read_b128 v[134:137], v0
	ds_read_b128 v[148:151], v0 offset:1024
	ds_read_b128 v[152:155], v0 offset:2048
	ds_read_b128 v[156:159], v0 offset:3072
	v_add_u32_e32 v0, s81, v180
	ds_read_b128 v[160:163], v0
	ds_read_b128 v[164:167], v0 offset:1024
	ds_read_b128 v[168:171], v0 offset:2048
	ds_read_b128 v[172:175], v0 offset:3072
	s_cmpk_eq_i32 s0, 0x700
	s_cselect_b32 s3, s47, s3
	s_cselect_b32 s2, s46, s2
	s_cselect_b32 s77, s39, s37
	s_cselect_b32 s76, s38, s7
	s_cselect_b32 s7, s73, s50
	v_lshl_add_u64 v[176:177], v[132:133], 0, s[0:1]
	s_add_i32 m0, s49, 0xc000
	ds_read_b128 v[182:185], v181
	ds_read_b128 v[186:189], v181 offset:1024
	ds_read_b128 v[190:193], v181 offset:2048
	ds_read_b128 v[194:197], v181 offset:3072
	ds_read_b128 v[198:201], v181 offset:4096
	ds_read_b128 v[202:205], v181 offset:5120
	ds_read_b128 v[206:209], v181 offset:6144
	ds_read_b128 v[210:213], v181 offset:7168
	global_load_lds_dwordx4 v[176:177], off
	v_lshl_add_u64 v[176:177], v[130:131], 0, s[0:1]
	s_add_i32 m0, s49, 0xe000
	s_nop 0
	global_load_lds_dwordx4 v[176:177], off
	s_waitcnt vmcnt(8)
	s_waitcnt lgkmcnt(0)
	s_barrier
	s_setprio 1
	v_mfma_f32_16x16x32_bf16 v[126:129], v[134:137], v[182:185], v[126:129]
	v_mfma_f32_16x16x32_bf16 v[122:125], v[152:155], v[182:185], v[122:125]
	v_mfma_f32_16x16x32_bf16 v[118:121], v[134:137], v[190:193], v[118:121]
	v_mfma_f32_16x16x32_bf16 v[114:117], v[152:155], v[190:193], v[114:117]
	v_mfma_f32_16x16x32_bf16 v[110:113], v[134:137], v[198:201], v[110:113]
	v_mfma_f32_16x16x32_bf16 v[106:109], v[152:155], v[198:201], v[106:109]
	v_mfma_f32_16x16x32_bf16 v[102:105], v[134:137], v[206:209], v[102:105]
	v_mfma_f32_16x16x32_bf16 v[98:101], v[152:155], v[206:209], v[98:101]
	v_mfma_f32_16x16x32_bf16 v[126:129], v[148:151], v[186:189], v[126:129]
	v_mfma_f32_16x16x32_bf16 v[122:125], v[156:159], v[186:189], v[122:125]
	v_mfma_f32_16x16x32_bf16 v[118:121], v[148:151], v[194:197], v[118:121]
	v_mfma_f32_16x16x32_bf16 v[114:117], v[156:159], v[194:197], v[114:117]
	v_mfma_f32_16x16x32_bf16 v[110:113], v[148:151], v[202:205], v[110:113]
	v_mfma_f32_16x16x32_bf16 v[106:109], v[156:159], v[202:205], v[106:109]
	v_mfma_f32_16x16x32_bf16 v[102:105], v[148:151], v[210:213], v[102:105]
	v_mfma_f32_16x16x32_bf16 v[98:101], v[156:159], v[210:213], v[98:101]
	v_mfma_f32_16x16x32_bf16 v[94:97], v[160:163], v[182:185], v[94:97]
	v_mfma_f32_16x16x32_bf16 v[90:93], v[168:171], v[182:185], v[90:93]
	v_mfma_f32_16x16x32_bf16 v[86:89], v[160:163], v[190:193], v[86:89]
	v_mfma_f32_16x16x32_bf16 v[82:85], v[168:171], v[190:193], v[82:85]
	v_mfma_f32_16x16x32_bf16 v[78:81], v[160:163], v[198:201], v[78:81]
	v_mfma_f32_16x16x32_bf16 v[74:77], v[168:171], v[198:201], v[74:77]
	v_mfma_f32_16x16x32_bf16 v[70:73], v[160:163], v[206:209], v[70:73]
	v_mfma_f32_16x16x32_bf16 v[66:69], v[168:171], v[206:209], v[66:69]
	v_mfma_f32_16x16x32_bf16 v[94:97], v[164:167], v[186:189], v[94:97]
	v_mfma_f32_16x16x32_bf16 v[90:93], v[172:175], v[186:189], v[90:93]
	v_mfma_f32_16x16x32_bf16 v[86:89], v[164:167], v[194:197], v[86:89]
	v_mfma_f32_16x16x32_bf16 v[82:85], v[172:175], v[194:197], v[82:85]
	v_mfma_f32_16x16x32_bf16 v[78:81], v[164:167], v[202:205], v[78:81]
	v_mfma_f32_16x16x32_bf16 v[74:77], v[172:175], v[202:205], v[74:77]
	v_mfma_f32_16x16x32_bf16 v[70:73], v[164:167], v[210:213], v[70:73]
	v_mfma_f32_16x16x32_bf16 v[66:69], v[172:175], v[210:213], v[66:69]
	s_setprio 0
	s_barrier
	s_add_i32 s37, s80, s48
	v_mad_u64_u32 v[176:177], s[78:79], s7, v139, v[138:139]
	s_mov_b32 m0, s37
	ds_read_b128 v[182:185], v181 offset:16384
	ds_read_b128 v[186:189], v181 offset:17408
	ds_read_b128 v[190:193], v181 offset:18432
	ds_read_b128 v[194:197], v181 offset:19456
	ds_read_b128 v[198:201], v181 offset:20480
	ds_read_b128 v[202:205], v181 offset:21504
	ds_read_b128 v[206:209], v181 offset:22528
	ds_read_b128 v[210:213], v181 offset:23552
	v_mov_b32_e32 v177, v1
	global_load_lds_dwordx4 v176, s[76:77]
	v_lshl_add_u32 v0, s7, 6, v176
	s_add_i32 m0, s37, 0x2000
	s_lshl_b32 s7, s7, 7
	v_lshl_add_u64 v[214:215], s[76:77], 0, v[176:177]
	v_lshl_add_u64 v[236:237], s[76:77], 0, v[0:1]
	global_load_lds_dwordx4 v0, s[76:77]
	s_add_u32 s76, s76, s7
	s_addc_u32 s77, s77, 0
	s_add_i32 s7, s81, s48
	s_mov_b32 m0, s7
	v_lshl_add_u64 v[246:247], s[2:3], 0, v[140:141]
	global_load_lds_dwordx4 v176, s[76:77]
	s_add_i32 m0, s7, 0x2000
	v_lshl_add_u64 v[248:249], s[2:3], 0, v[142:143]
	global_load_lds_dwordx4 v0, s[76:77]
	s_mov_b32 m0, s49
	v_lshl_add_u64 v[238:239], s[76:77], 0, v[176:177]
	global_load_lds_dwordx4 v[246:247], off
	s_mov_b32 m0, s51
	v_lshl_add_u64 v[176:177], s[76:77], 0, v[0:1]
	global_load_lds_dwordx4 v[248:249], off
	s_waitcnt vmcnt(8)
	s_waitcnt lgkmcnt(0)
	s_barrier
	s_setprio 1
	v_mfma_f32_16x16x32_bf16 v[62:65], v[134:137], v[182:185], v[62:65]
	v_mfma_f32_16x16x32_bf16 v[58:61], v[152:155], v[182:185], v[58:61]
	v_mfma_f32_16x16x32_bf16 v[54:57], v[134:137], v[190:193], v[54:57]
	v_mfma_f32_16x16x32_bf16 v[50:53], v[152:155], v[190:193], v[50:53]
	v_mfma_f32_16x16x32_bf16 v[46:49], v[134:137], v[198:201], v[46:49]
	v_mfma_f32_16x16x32_bf16 v[42:45], v[152:155], v[198:201], v[42:45]
	v_mfma_f32_16x16x32_bf16 v[38:41], v[134:137], v[206:209], v[38:41]
	v_mfma_f32_16x16x32_bf16 v[34:37], v[152:155], v[206:209], v[34:37]
	v_mfma_f32_16x16x32_bf16 v[62:65], v[148:151], v[186:189], v[62:65]
	v_mfma_f32_16x16x32_bf16 v[58:61], v[156:159], v[186:189], v[58:61]
	v_mfma_f32_16x16x32_bf16 v[54:57], v[148:151], v[194:197], v[54:57]
	v_mfma_f32_16x16x32_bf16 v[50:53], v[156:159], v[194:197], v[50:53]
	v_mfma_f32_16x16x32_bf16 v[46:49], v[148:151], v[202:205], v[46:49]
	v_mfma_f32_16x16x32_bf16 v[42:45], v[156:159], v[202:205], v[42:45]
	v_mfma_f32_16x16x32_bf16 v[38:41], v[148:151], v[210:213], v[38:41]
	v_mfma_f32_16x16x32_bf16 v[34:37], v[156:159], v[210:213], v[34:37]
	v_mfma_f32_16x16x32_bf16 v[30:33], v[160:163], v[182:185], v[30:33]
	v_mfma_f32_16x16x32_bf16 v[26:29], v[168:171], v[182:185], v[26:29]
	v_mfma_f32_16x16x32_bf16 v[22:25], v[160:163], v[190:193], v[22:25]
	v_mfma_f32_16x16x32_bf16 v[18:21], v[168:171], v[190:193], v[18:21]
	v_mfma_f32_16x16x32_bf16 v[14:17], v[160:163], v[198:201], v[14:17]
	v_mfma_f32_16x16x32_bf16 v[10:13], v[168:171], v[198:201], v[10:13]
	v_mfma_f32_16x16x32_bf16 v[6:9], v[160:163], v[206:209], v[6:9]
	v_mfma_f32_16x16x32_bf16 v[2:5], v[168:171], v[206:209], v[2:5]
	v_mfma_f32_16x16x32_bf16 v[30:33], v[164:167], v[186:189], v[30:33]
	v_mfma_f32_16x16x32_bf16 v[26:29], v[172:175], v[186:189], v[26:29]
	v_mfma_f32_16x16x32_bf16 v[22:25], v[164:167], v[194:197], v[22:25]
	v_mfma_f32_16x16x32_bf16 v[18:21], v[172:175], v[194:197], v[18:21]
	v_mfma_f32_16x16x32_bf16 v[14:17], v[164:167], v[202:205], v[14:17]
	v_mfma_f32_16x16x32_bf16 v[10:13], v[172:175], v[202:205], v[10:13]
	v_mfma_f32_16x16x32_bf16 v[6:9], v[164:167], v[210:213], v[6:9]
	v_mfma_f32_16x16x32_bf16 v[2:5], v[172:175], v[210:213], v[2:5]
	s_setprio 0
	s_barrier
	s_add_i32 s7, 0, 0x18000
	v_add_u32_e32 v0, s7, v180
	s_add_i32 s37, 0, 0x1c000
	ds_read_b128 v[134:137], v0
	ds_read_b128 v[148:151], v0 offset:1024
	ds_read_b128 v[152:155], v0 offset:2048
	ds_read_b128 v[156:159], v0 offset:3072
	v_add_u32_e32 v0, s37, v180
	ds_read_b128 v[160:163], v0
	ds_read_b128 v[164:167], v0 offset:1024
	ds_read_b128 v[168:171], v0 offset:2048
	ds_read_b128 v[172:175], v0 offset:3072
	s_add_u32 s2, s2, 0x40000
	s_addc_u32 s3, s3, 0
	s_mov_b32 m0, s52
	v_lshl_add_u64 v[244:245], s[2:3], 0, v[140:141]
	ds_read_b128 v[182:185], v181 offset:32768
	ds_read_b128 v[186:189], v181 offset:33792
	ds_read_b128 v[190:193], v181 offset:34816
	ds_read_b128 v[194:197], v181 offset:35840
	ds_read_b128 v[198:201], v181 offset:36864
	ds_read_b128 v[202:205], v181 offset:37888
	ds_read_b128 v[206:209], v181 offset:38912
	ds_read_b128 v[210:213], v181 offset:39936
	global_load_lds_dwordx4 v[244:245], off
	v_lshl_add_u64 v[244:245], s[2:3], 0, v[142:143]
	s_mov_b32 m0, s53
	s_nop 0
	global_load_lds_dwordx4 v[244:245], off
	s_waitcnt vmcnt(8)
	s_waitcnt lgkmcnt(0)
	s_barrier
	s_setprio 1
	v_mfma_f32_16x16x32_bf16 v[126:129], v[134:137], v[182:185], v[126:129]
	v_mfma_f32_16x16x32_bf16 v[122:125], v[152:155], v[182:185], v[122:125]
	v_mfma_f32_16x16x32_bf16 v[118:121], v[134:137], v[190:193], v[118:121]
	v_mfma_f32_16x16x32_bf16 v[114:117], v[152:155], v[190:193], v[114:117]
	v_mfma_f32_16x16x32_bf16 v[110:113], v[134:137], v[198:201], v[110:113]
	v_mfma_f32_16x16x32_bf16 v[106:109], v[152:155], v[198:201], v[106:109]
	v_mfma_f32_16x16x32_bf16 v[102:105], v[134:137], v[206:209], v[102:105]
	v_mfma_f32_16x16x32_bf16 v[98:101], v[152:155], v[206:209], v[98:101]
	v_mfma_f32_16x16x32_bf16 v[126:129], v[148:151], v[186:189], v[126:129]
	v_mfma_f32_16x16x32_bf16 v[122:125], v[156:159], v[186:189], v[122:125]
	v_mfma_f32_16x16x32_bf16 v[118:121], v[148:151], v[194:197], v[118:121]
	v_mfma_f32_16x16x32_bf16 v[114:117], v[156:159], v[194:197], v[114:117]
	v_mfma_f32_16x16x32_bf16 v[110:113], v[148:151], v[202:205], v[110:113]
	v_mfma_f32_16x16x32_bf16 v[106:109], v[156:159], v[202:205], v[106:109]
	v_mfma_f32_16x16x32_bf16 v[102:105], v[148:151], v[210:213], v[102:105]
	v_mfma_f32_16x16x32_bf16 v[98:101], v[156:159], v[210:213], v[98:101]
	v_mfma_f32_16x16x32_bf16 v[94:97], v[160:163], v[182:185], v[94:97]
	v_mfma_f32_16x16x32_bf16 v[90:93], v[168:171], v[182:185], v[90:93]
	v_mfma_f32_16x16x32_bf16 v[86:89], v[160:163], v[190:193], v[86:89]
	v_mfma_f32_16x16x32_bf16 v[82:85], v[168:171], v[190:193], v[82:85]
	v_mfma_f32_16x16x32_bf16 v[78:81], v[160:163], v[198:201], v[78:81]
	v_mfma_f32_16x16x32_bf16 v[74:77], v[168:171], v[198:201], v[74:77]
	v_mfma_f32_16x16x32_bf16 v[70:73], v[160:163], v[206:209], v[70:73]
	v_mfma_f32_16x16x32_bf16 v[66:69], v[168:171], v[206:209], v[66:69]
	v_mfma_f32_16x16x32_bf16 v[94:97], v[164:167], v[186:189], v[94:97]
	v_mfma_f32_16x16x32_bf16 v[90:93], v[172:175], v[186:189], v[90:93]
	v_mfma_f32_16x16x32_bf16 v[86:89], v[164:167], v[194:197], v[86:89]
	v_mfma_f32_16x16x32_bf16 v[82:85], v[172:175], v[194:197], v[82:85]
	v_mfma_f32_16x16x32_bf16 v[78:81], v[164:167], v[202:205], v[78:81]
	v_mfma_f32_16x16x32_bf16 v[74:77], v[172:175], v[202:205], v[74:77]
	v_mfma_f32_16x16x32_bf16 v[70:73], v[164:167], v[210:213], v[70:73]
	v_mfma_f32_16x16x32_bf16 v[66:69], v[172:175], v[210:213], v[66:69]
	s_setprio 0
	s_barrier
	s_add_i32 s2, s7, s48
	v_lshl_add_u64 v[214:215], v[214:215], 0, s[42:43]
	s_mov_b32 m0, s2
	ds_read_b128 v[182:185], v181 offset:49152
	ds_read_b128 v[186:189], v181 offset:50176
	ds_read_b128 v[190:193], v181 offset:51200
	ds_read_b128 v[194:197], v181 offset:52224
	ds_read_b128 v[198:201], v181 offset:53248
	ds_read_b128 v[202:205], v181 offset:54272
	ds_read_b128 v[206:209], v181 offset:55296
	ds_read_b128 v[210:213], v181 offset:56320
	global_load_lds_dwordx4 v[214:215], off
	v_lshl_add_u64 v[214:215], v[236:237], 0, s[42:43]
	s_add_i32 m0, s2, 0x2000
	s_add_i32 s2, s37, s48
	global_load_lds_dwordx4 v[214:215], off
	v_lshl_add_u64 v[214:215], v[238:239], 0, s[42:43]
	s_mov_b32 m0, s2
	v_lshl_add_u64 v[176:177], v[176:177], 0, s[42:43]
	global_load_lds_dwordx4 v[214:215], off
	s_add_i32 m0, s2, 0x2000
	s_nop 0
	global_load_lds_dwordx4 v[176:177], off
	v_lshl_add_u64 v[176:177], v[246:247], 0, s[42:43]
	s_mov_b32 m0, s56
	s_nop 0
	global_load_lds_dwordx4 v[176:177], off
	v_lshl_add_u64 v[176:177], v[248:249], 0, s[42:43]
	s_mov_b32 m0, s57
	s_nop 0
	global_load_lds_dwordx4 v[176:177], off
	s_waitcnt vmcnt(8)
	s_waitcnt lgkmcnt(0)
	s_barrier
	s_setprio 1
	v_mfma_f32_16x16x32_bf16 v[62:65], v[134:137], v[182:185], v[62:65]
	v_mfma_f32_16x16x32_bf16 v[58:61], v[152:155], v[182:185], v[58:61]
	v_mfma_f32_16x16x32_bf16 v[54:57], v[134:137], v[190:193], v[54:57]
	v_mfma_f32_16x16x32_bf16 v[50:53], v[152:155], v[190:193], v[50:53]
	v_mfma_f32_16x16x32_bf16 v[46:49], v[134:137], v[198:201], v[46:49]
	v_mfma_f32_16x16x32_bf16 v[42:45], v[152:155], v[198:201], v[42:45]
	v_mfma_f32_16x16x32_bf16 v[38:41], v[134:137], v[206:209], v[38:41]
	v_mfma_f32_16x16x32_bf16 v[34:37], v[152:155], v[206:209], v[34:37]
	v_mfma_f32_16x16x32_bf16 v[62:65], v[148:151], v[186:189], v[62:65]
	v_mfma_f32_16x16x32_bf16 v[58:61], v[156:159], v[186:189], v[58:61]
	v_mfma_f32_16x16x32_bf16 v[54:57], v[148:151], v[194:197], v[54:57]
	v_mfma_f32_16x16x32_bf16 v[50:53], v[156:159], v[194:197], v[50:53]
	v_mfma_f32_16x16x32_bf16 v[46:49], v[148:151], v[202:205], v[46:49]
	v_mfma_f32_16x16x32_bf16 v[42:45], v[156:159], v[202:205], v[42:45]
	v_mfma_f32_16x16x32_bf16 v[38:41], v[148:151], v[210:213], v[38:41]
	v_mfma_f32_16x16x32_bf16 v[34:37], v[156:159], v[210:213], v[34:37]
	v_mfma_f32_16x16x32_bf16 v[30:33], v[160:163], v[182:185], v[30:33]
	v_mfma_f32_16x16x32_bf16 v[26:29], v[168:171], v[182:185], v[26:29]
	v_mfma_f32_16x16x32_bf16 v[22:25], v[160:163], v[190:193], v[22:25]
	v_mfma_f32_16x16x32_bf16 v[18:21], v[168:171], v[190:193], v[18:21]
	v_mfma_f32_16x16x32_bf16 v[14:17], v[160:163], v[198:201], v[14:17]
	v_mfma_f32_16x16x32_bf16 v[10:13], v[168:171], v[198:201], v[10:13]
	v_mfma_f32_16x16x32_bf16 v[6:9], v[160:163], v[206:209], v[6:9]
	v_mfma_f32_16x16x32_bf16 v[2:5], v[168:171], v[206:209], v[2:5]
	v_mfma_f32_16x16x32_bf16 v[30:33], v[164:167], v[186:189], v[30:33]
	v_mfma_f32_16x16x32_bf16 v[26:29], v[172:175], v[186:189], v[26:29]
	v_mfma_f32_16x16x32_bf16 v[22:25], v[164:167], v[194:197], v[22:25]
	v_mfma_f32_16x16x32_bf16 v[18:21], v[172:175], v[194:197], v[18:21]
	v_mfma_f32_16x16x32_bf16 v[14:17], v[164:167], v[202:205], v[14:17]
	v_mfma_f32_16x16x32_bf16 v[10:13], v[172:175], v[202:205], v[10:13]
	v_mfma_f32_16x16x32_bf16 v[6:9], v[164:167], v[210:213], v[6:9]
	v_mfma_f32_16x16x32_bf16 v[2:5], v[172:175], v[210:213], v[2:5]
	s_setprio 0
	s_barrier
	s_add_i32 s6, s6, 2
	s_add_u32 s0, s0, 0x100
	s_addc_u32 s1, s1, 0
	s_cmp_gt_u32 s6, 13
	s_cbranch_scc0 .LBB0_1026
	s_and_b64 vcc, exec, s[18:19]
	s_cbranch_vccz .LBB0_1029
	s_barrier
